# v16 + each unit's first 16 fragment ds_reads hoisted above the unit-header scalar chain (header overlaps LDS latency)
# speedup vs baseline: 1.0032x; 1.0005x over previous
;     __device__ __forceinline__ bool next(int i, Unit& u) const { const int ti = i / 3, sg = i - 3 * ti; if (!StaticOrder::next(ti, u)) return false; u.seg = sg; return true; }
;     __host__ __device__ __forceinline__ bool next(int i, Unit& u) const {
;         const long L = (long)i * G + c; if (L >= nwg) return false;
;         int wgid = (int)L; { const int q = nwg / NXCD, r = nwg % NXCD, xcd = wgid % NXCD, off = wgid / NXCD; wgid = (xcd < r ? xcd * (q + 1) : r * (q + 1) + (xcd - r) * q) + off; }
;         const int nig = WGM * nN, gid = wgid / nig, fm = gid * WGM, gsz = (nM - fm) < WGM ? (nM - fm) : WGM;
;         u.pm = fm + ((wgid % nig) % gsz); u.pn = (wgid % nig) / gsz; u.seg = 0; return true;
;     }
.LBB0_535:
	v_add_u32_e32 v162, 0x10000, v153
	ds_read_b128 v[142:145], v162
	ds_read_b128 v[146:149], v162 offset:1024
	ds_read_b128 v[158:161], v162 offset:2048
	ds_read_b128 v[186:189], v162 offset:3072
	ds_read_b128 v[190:193], v162 offset:16384
	ds_read_b128 v[194:197], v162 offset:17408
	ds_read_b128 v[198:201], v162 offset:18432
	ds_read_b128 v[202:205], v162 offset:19456
	ds_read_b128 v[206:209], v156
	ds_read_b128 v[210:213], v156 offset:1024
	ds_read_b128 v[214:217], v156 offset:2048
	ds_read_b128 v[218:221], v156 offset:3072
	ds_read_b128 v[222:225], v156 offset:4096
	ds_read_b128 v[234:237], v156 offset:5120
	ds_read_b128 v[238:241], v156 offset:6144
	ds_read_b128 v[242:245], v156 offset:7168
	s_add_i32 s8, s8, 1
	s_mul_i32 s6, s8, s12
	s_mul_hi_u32 s15, s8, s78
	s_add_i32 s15, s15, s6
	s_mul_i32 s6, s8, s78
	s_add_u32 s58, s6, s77
	s_addc_u32 s59, s15, s13
	v_cmp_gt_i64_e32 vcc, s[58:59], v[166:167]
	v_cmp_lt_i64_e64 s[42:43], s[58:59], v[164:165]
	s_cbranch_vccnz .LBB0_537
	s_ashr_i32 s6, s58, 31
	s_lshr_b32 s6, s6, 29
	s_add_i32 s6, s58, s6
	s_ashr_i32 s15, s6, 3
	s_and_b32 s6, s6, -8
	s_sub_i32 s6, s58, s6
	s_cmp_lt_i32 s6, 0
	s_movk_i32 s34, 0x161
	s_cselect_b32 s34, s34, 0x160
	s_mul_i32 s6, s6, s34
	s_add_i32 s6, s6, s15
	s_mul_hi_i32 s15, s6, 0x2e8ba2e9
	s_lshr_b32 s34, s15, 31
	s_ashr_i32 s15, s15, 6
	s_add_i32 s15, s15, s34
	s_lshl_b32 s34, s15, 3
	s_sub_i32 s35, 64, s34
	s_min_i32 s35, s35, 8
	s_abs_i32 s45, s35
	v_cvt_f32_u32_e32 v2, s45
	s_sub_i32 s55, 0, s45
	s_mulk_i32 s15, 0x160
	s_sub_i32 s6, s6, s15
	v_rcp_iflag_f32_e32 v2, v2
	s_abs_i32 s15, s6
	s_xor_b32 s54, s6, s35
	s_ashr_i32 s54, s54, 31
	v_mul_f32_e32 v2, 0x4f7ffffe, v2
	v_cvt_u32_f32_e32 v2, v2
	s_nop 0
	v_readfirstlane_b32 s56, v2
	s_mul_i32 s55, s55, s56
	s_mul_hi_u32 s55, s56, s55
	s_add_i32 s56, s56, s55
	s_mul_hi_u32 s55, s15, s56
	s_mul_i32 s56, s55, s45
	s_sub_i32 s15, s15, s56
	s_add_i32 s57, s55, 1
	s_sub_i32 s56, s15, s45
	s_cmp_ge_u32 s15, s45
	s_cselect_b32 s55, s57, s55
	s_cselect_b32 s15, s56, s15
	s_add_i32 s56, s55, 1
	s_cmp_ge_u32 s15, s45
	s_cselect_b32 s15, s56, s55
	s_xor_b32 s15, s15, s54
	s_sub_i32 s54, s15, s54
	s_mul_i32 s15, s54, s35
	s_sub_i32 s6, s6, s15
	s_add_i32 s56, s34, s6
;     __device__ __forceinline__ const char* pa(const Gemm& g, const Unit& u, size_t tstep) const { return (const char*)g.A + (size_t)u.pm * tstep; }
;     __device__ __forceinline__ const char* pb(const Gemm& g, const Unit& u, size_t tstep) const { return (const char*)g.Bt + (size_t)u.pn * tstep; }
;     __device__ __forceinline__ const char* pa(const Gemm& g, const Unit& u, size_t tstep) const { return (const char*)g.A + (size_t)(u.pn >> 1) * 512 + (size_t)u.pm * tstep; }
;     __device__ __forceinline__ const char* pa(const Gemm& g, const Unit& u, size_t tstep) const { return (const char*)g.A + (size_t)u.seg * astride + (size_t)u.pm * tstep; }
;     __device__ __forceinline__ const char* pb(const Gemm& g, const Unit& u, size_t tstep) const { return (const char*)g.Bt + (size_t)u.seg * bstride + (size_t)u.pn * tstep; }
; #define PG8_STAGE(bufoff, gbase, voff) do { _Pragma("unroll") for (int _i = 0; _i < 2; ++_i) \
;         __builtin_amdgcn_global_load_lds((const unsigned*)((const char*)(gbase) + (voff)[_i]), (PG8_LAS unsigned*)(lds + (bufoff) + ldsw + _i * 8192), 16, 0, 0); } while (0)
; #define PG8_WAIT_V(n) asm volatile("s_waitcnt vmcnt(" #n ")" ::: "memory")
; #define PG8_WAIT_L(n) asm volatile("s_waitcnt lgkmcnt(" #n ")" ::: "memory")
; #define PG8_BAR __builtin_amdgcn_s_barrier()
;     ...
;         const char* nA = has_next ? S.pa(g, nxt, tstepA) : cA; const char* nB = has_next ? S.pb(g, nxt, tstepB) : cB;
;         for (int t = 0; t < nt; t += 2) {
;             const bool last = (t == nt - 2);
;             const char* a1 = cA + (size_t)(t + 1) * kstep;
;             const char* a2 = last ? nA : cA + (size_t)(t + 2) * kstep; const char* b2 = last ? nB : cB + (size_t)(t + 2) * kstep;
;             const char* a3 = a2 + kstep; const char* b3 = b2 + kstep;
;             if (last && has_next) S.a_ready(nxt);
;             if constexpr (SP2) {
;             PG8_LDB(B0, 0, 0); PG8_LDB(B1, 0, 1); PG8_SCHED; PG8_LDA(At, 0, 0); PG8_STAGE(PG8_SA(1, 1), a1 + hstepA, voffA);
;             PG8_WAIT_V(8); PG8_WAIT_L(0); PG8_BAR; PG8_MMA(0, 0, At, B0); PG8_MMA(0, 1, At, B1); PG8_BAR; PG8_SCHED;
;             PG8_LDA(At, 0, 1); PG8_STAGE(PG8_SB(0, 0), b2, voffB); PG8_STAGE(PG8_SB(0, 1), b2 + hstepB, voffB); PG8_STAGE(PG8_SA(0, 0), a2, voffA);
;             PG8_WAIT_V(8); PG8_WAIT_L(0); PG8_BAR; PG8_MMA(1, 0, At, B0); PG8_MMA(1, 1, At, B1); PG8_BAR; PG8_SCHED;
.LBB0_537:
	s_ashr_i32 s57, s56, 31
	s_lshl_b64 s[34:35], s[56:57], 19
	s_add_u32 s58, s11, s34
	s_addc_u32 s59, s24, s35
	s_and_b64 s[34:35], s[42:43], exec
	s_cselect_b32 s6, s59, s65
	s_cselect_b32 s15, s58, s64
	s_ashr_i32 s55, s54, 31
	s_lshl_b64 s[34:35], s[54:55], 19
	s_add_u32 s60, s79, s34
	s_addc_u32 s61, s80, s35
	s_and_b64 s[34:35], s[42:43], exec
	s_cselect_b32 s34, s61, s67
	s_cselect_b32 s35, s60, s66
	s_add_u32 s64, s64, 0x40080
	s_addc_u32 s65, s65, 0
	s_add_u32 s45, s66, 0x100
	s_addc_u32 s55, s67, 0
	s_mov_b32 s57, -2
	s_waitcnt lgkmcnt(0)
	s_add_u32 s63, s64, 0xfffc0080
	s_addc_u32 s66, s65, -1
	s_add_i32 s68, 0, 0x10000
	s_cmp_eq_u32 s57, 12
	s_cselect_b32 s75, s6, s66
	s_cselect_b32 s74, s15, s63
	s_cselect_b32 s67, s34, s55
	s_cselect_b32 s66, s35, s45
	s_add_i32 s63, 0, 0x14000
	s_add_i32 m0, s81, 0xc000
	global_load_lds_dwordx4 v138, s[64:65]
	s_add_i32 m0, s81, 0xe000
	s_nop 0
	global_load_lds_dwordx4 v140, s[64:65]
	s_waitcnt vmcnt(8)
	s_waitcnt lgkmcnt(0)
	s_barrier
	v_mfma_i32_16x16x64_i8 v[128:131], v[142:145], v[206:209], 0
	v_mfma_i32_16x16x64_i8 v[120:123], v[158:161], v[206:209], 0
	v_mfma_i32_16x16x64_i8 v[112:115], v[142:145], v[214:217], 0
	v_mfma_i32_16x16x64_i8 v[104:107], v[158:161], v[214:217], 0
	v_mfma_i32_16x16x64_i8 v[96:99], v[142:145], v[222:225], 0
	v_mfma_i32_16x16x64_i8 v[88:91], v[158:161], v[222:225], 0
	v_mfma_i32_16x16x64_i8 v[80:83], v[142:145], v[238:241], 0
	v_mfma_i32_16x16x64_i8 v[72:75], v[158:161], v[238:241], 0
	v_mfma_i32_16x16x64_i8 v[128:131], v[146:149], v[210:213], v[128:131]
	v_mfma_i32_16x16x64_i8 v[120:123], v[186:189], v[210:213], v[120:123]
	v_mfma_i32_16x16x64_i8 v[112:115], v[146:149], v[218:221], v[112:115]
	v_mfma_i32_16x16x64_i8 v[104:107], v[186:189], v[218:221], v[104:107]
	v_mfma_i32_16x16x64_i8 v[96:99], v[146:149], v[234:237], v[96:99]
	v_mfma_i32_16x16x64_i8 v[88:91], v[186:189], v[234:237], v[88:91]
	v_mfma_i32_16x16x64_i8 v[80:83], v[146:149], v[242:245], v[80:83]
	v_mfma_i32_16x16x64_i8 v[72:75], v[186:189], v[242:245], v[72:75]
	v_mfma_i32_16x16x64_i8 v[124:127], v[190:193], v[206:209], 0
	v_mfma_i32_16x16x64_i8 v[116:119], v[198:201], v[206:209], 0
	v_mfma_i32_16x16x64_i8 v[108:111], v[190:193], v[214:217], 0
	v_mfma_i32_16x16x64_i8 v[100:103], v[198:201], v[214:217], 0
	v_mfma_i32_16x16x64_i8 v[92:95], v[190:193], v[222:225], 0
	v_mfma_i32_16x16x64_i8 v[84:87], v[198:201], v[222:225], 0
	v_mfma_i32_16x16x64_i8 v[76:79], v[190:193], v[238:241], 0
	v_mfma_i32_16x16x64_i8 v[68:71], v[198:201], v[238:241], 0
	v_mfma_i32_16x16x64_i8 v[124:127], v[194:197], v[210:213], v[124:127]
	v_mfma_i32_16x16x64_i8 v[116:119], v[202:205], v[210:213], v[116:119]
	v_mfma_i32_16x16x64_i8 v[108:111], v[194:197], v[218:221], v[108:111]
	v_mfma_i32_16x16x64_i8 v[100:103], v[202:205], v[218:221], v[100:103]
	v_mfma_i32_16x16x64_i8 v[92:95], v[194:197], v[234:237], v[92:95]
	v_mfma_i32_16x16x64_i8 v[84:87], v[202:205], v[234:237], v[84:87]
	v_mfma_i32_16x16x64_i8 v[76:79], v[194:197], v[242:245], v[76:79]
	v_mfma_i32_16x16x64_i8 v[68:71], v[202:205], v[242:245], v[68:71]
	s_barrier
	s_add_i32 s68, s68, s10
	s_mov_b32 m0, s68
	ds_read_b128 v[206:209], v156 offset:16384
	ds_read_b128 v[210:213], v156 offset:17408
	ds_read_b128 v[214:217], v156 offset:18432
	ds_read_b128 v[218:221], v156 offset:19456
	ds_read_b128 v[222:225], v156 offset:20480
	ds_read_b128 v[234:237], v156 offset:21504
	ds_read_b128 v[238:241], v156 offset:22528
	ds_read_b128 v[242:245], v156 offset:23552
	global_load_lds_dwordx4 v34, s[66:67]
	s_add_i32 m0, s68, 0x2000
	s_add_u32 s70, s66, 0x40000
	s_addc_u32 s71, s67, 0
	s_add_i32 s63, s63, s10
	global_load_lds_dwordx4 v136, s[66:67]
	s_mov_b32 m0, s63
	s_nop 0
	global_load_lds_dwordx4 v34, s[70:71]
	s_add_i32 m0, s63, 0x2000
	s_nop 0
	global_load_lds_dwordx4 v136, s[70:71]
	s_mov_b32 m0, s81
	s_nop 0
	global_load_lds_dwordx4 v132, s[74:75]
	s_mov_b32 m0, s82
	s_nop 0
	global_load_lds_dwordx4 v134, s[74:75]
	s_waitcnt vmcnt(8)
	s_waitcnt lgkmcnt(0)
	s_barrier
	v_mfma_i32_16x16x64_i8 v[64:67], v[142:145], v[206:209], 0
	v_mfma_i32_16x16x64_i8 v[56:59], v[158:161], v[206:209], 0
	v_mfma_i32_16x16x64_i8 v[48:51], v[142:145], v[214:217], 0
	v_mfma_i32_16x16x64_i8 v[40:43], v[158:161], v[214:217], 0
	v_mfma_i32_16x16x64_i8 v[30:33], v[142:145], v[222:225], 0
	v_mfma_i32_16x16x64_i8 v[22:25], v[158:161], v[222:225], 0
	v_mfma_i32_16x16x64_i8 v[14:17], v[142:145], v[238:241], 0
	v_mfma_i32_16x16x64_i8 v[6:9], v[158:161], v[238:241], 0
	v_mfma_i32_16x16x64_i8 v[64:67], v[146:149], v[210:213], v[64:67]
	v_mfma_i32_16x16x64_i8 v[56:59], v[186:189], v[210:213], v[56:59]
	v_mfma_i32_16x16x64_i8 v[48:51], v[146:149], v[218:221], v[48:51]
	v_mfma_i32_16x16x64_i8 v[40:43], v[186:189], v[218:221], v[40:43]
	v_mfma_i32_16x16x64_i8 v[30:33], v[146:149], v[234:237], v[30:33]
	v_mfma_i32_16x16x64_i8 v[22:25], v[186:189], v[234:237], v[22:25]
	v_mfma_i32_16x16x64_i8 v[14:17], v[146:149], v[242:245], v[14:17]
	v_mfma_i32_16x16x64_i8 v[6:9], v[186:189], v[242:245], v[6:9]
	v_mfma_i32_16x16x64_i8 v[60:63], v[190:193], v[206:209], 0
	v_mfma_i32_16x16x64_i8 v[52:55], v[198:201], v[206:209], 0
	v_mfma_i32_16x16x64_i8 v[44:47], v[190:193], v[214:217], 0
	v_mfma_i32_16x16x64_i8 v[36:39], v[198:201], v[214:217], 0
	v_mfma_i32_16x16x64_i8 v[26:29], v[190:193], v[222:225], 0
	v_mfma_i32_16x16x64_i8 v[18:21], v[198:201], v[222:225], 0
	v_mfma_i32_16x16x64_i8 v[10:13], v[190:193], v[238:241], 0
	v_mfma_i32_16x16x64_i8 v[2:5], v[198:201], v[238:241], 0
	v_mfma_i32_16x16x64_i8 v[60:63], v[194:197], v[210:213], v[60:63]
	v_mfma_i32_16x16x64_i8 v[52:55], v[202:205], v[210:213], v[52:55]
	v_mfma_i32_16x16x64_i8 v[44:47], v[194:197], v[218:221], v[44:47]
	v_mfma_i32_16x16x64_i8 v[36:39], v[202:205], v[218:221], v[36:39]
	v_mfma_i32_16x16x64_i8 v[26:29], v[194:197], v[234:237], v[26:29]
	v_mfma_i32_16x16x64_i8 v[18:21], v[202:205], v[234:237], v[18:21]
	v_mfma_i32_16x16x64_i8 v[10:13], v[194:197], v[242:245], v[10:13]
	v_mfma_i32_16x16x64_i8 v[2:5], v[202:205], v[242:245], v[2:5]
	s_barrier
	s_branch .Lpeel_mid_538
	.p2align	6

;     __device__ __forceinline__ bool next(int i, Unit& u) const { const int ti = i / 3, sg = i - 3 * ti; if (!StaticOrder::next(ti, u)) return false; u.seg = sg; return true; }
;     __host__ __device__ __forceinline__ bool next(int i, Unit& u) const {
;         const long L = (long)i * G + c; if (L >= nwg) return false;
;         int wgid = (int)L; { const int q = nwg / NXCD, r = nwg % NXCD, xcd = wgid % NXCD, off = wgid / NXCD; wgid = (xcd < r ? xcd * (q + 1) : r * (q + 1) + (xcd - r) * q) + off; }
;         const int nig = WGM * nN, gid = wgid / nig, fm = gid * WGM, gsz = (nM - fm) < WGM ? (nM - fm) : WGM;
;         u.pm = fm + ((wgid % nig) % gsz); u.pn = (wgid % nig) / gsz; u.seg = 0; return true;
;     }
.LBB0_605:
	v_add_u32_e32 v226, 0x10000, v145
	ds_read_b128 v[148:151], v226
	ds_read_b128 v[152:155], v226 offset:1024
	ds_read_b128 v[156:159], v226 offset:2048
	ds_read_b128 v[160:163], v226 offset:3072
	ds_read_b128 v[186:189], v226 offset:16384
	ds_read_b128 v[190:193], v226 offset:17408
	ds_read_b128 v[194:197], v226 offset:18432
	ds_read_b128 v[198:201], v226 offset:19456
	ds_read_b128 v[202:205], v147
	ds_read_b128 v[206:209], v147 offset:1024
	ds_read_b128 v[210:213], v147 offset:2048
	ds_read_b128 v[214:217], v147 offset:3072
	ds_read_b128 v[218:221], v147 offset:4096
	ds_read_b128 v[222:225], v147 offset:5120
	ds_read_b128 v[234:237], v147 offset:6144
	ds_read_b128 v[238:241], v147 offset:7168
	s_add_i32 s56, s56, 1
	s_mul_i32 s31, s56, s45
	s_mul_hi_u32 s37, s56, s78
	s_add_i32 s37, s37, s31
	s_mul_i32 s31, s56, s78
	s_add_u32 s40, s31, s77
	s_addc_u32 s41, s37, s11
	v_cmp_gt_i64_e32 vcc, s[40:41], v[166:167]
	v_cmp_lt_i64_e64 s[38:39], s[40:41], v[164:165]
	s_cbranch_vccnz .LBB0_607
	s_ashr_i32 s30, s40, 31
	s_lshr_b32 s30, s30, 29
	s_add_i32 s30, s40, s30
	s_ashr_i32 s31, s30, 3
	s_and_b32 s30, s30, -8
	s_sub_i32 s30, s40, s30
	s_cmp_lt_i32 s30, 0
	s_movk_i32 s36, 0x161
	s_cselect_b32 s36, s36, 0x160
	s_mul_i32 s30, s30, s36
	s_add_i32 s30, s30, s31
	s_mul_hi_i32 s31, s30, 0x2e8ba2e9
	s_lshr_b32 s36, s31, 31
	s_ashr_i32 s31, s31, 6
	s_add_i32 s31, s31, s36
	s_lshl_b32 s36, s31, 3
	s_sub_i32 s37, 64, s36
	s_min_i32 s37, s37, 8
	s_abs_i32 s40, s37
	v_cvt_f32_u32_e32 v2, s40
	s_sub_i32 s42, 0, s40
	s_mulk_i32 s31, 0x160
	s_sub_i32 s31, s30, s31
	v_rcp_iflag_f32_e32 v2, v2
	s_abs_i32 s30, s31
	s_xor_b32 s41, s31, s37
	s_ashr_i32 s41, s41, 31
	v_mul_f32_e32 v2, 0x4f7ffffe, v2
	v_cvt_u32_f32_e32 v2, v2
	s_nop 0
	v_readfirstlane_b32 s43, v2
	s_mul_i32 s42, s42, s43
	s_mul_hi_u32 s42, s43, s42
	s_add_i32 s43, s43, s42
	s_mul_hi_u32 s42, s30, s43
	s_mul_i32 s43, s42, s40
	s_sub_i32 s30, s30, s43
	s_add_i32 s54, s42, 1
	s_sub_i32 s43, s30, s40
	s_cmp_ge_u32 s30, s40
	s_cselect_b32 s42, s54, s42
	s_cselect_b32 s30, s43, s30
	s_add_i32 s43, s42, 1
	s_cmp_ge_u32 s30, s40
	s_cselect_b32 s30, s43, s42
	s_xor_b32 s30, s30, s41
	s_sub_i32 s30, s30, s41
	s_mul_i32 s37, s30, s37
	s_sub_i32 s31, s31, s37
	s_add_i32 s36, s36, s31
;     __device__ __forceinline__ const char* pa(const Gemm& g, const Unit& u, size_t tstep) const { return (const char*)g.A + (size_t)u.pm * tstep; }
;     __device__ __forceinline__ const char* pb(const Gemm& g, const Unit& u, size_t tstep) const { return (const char*)g.Bt + (size_t)u.pn * tstep; }
;     __device__ __forceinline__ const char* pa(const Gemm& g, const Unit& u, size_t tstep) const { return (const char*)g.A + (size_t)(u.pn >> 1) * 512 + (size_t)u.pm * tstep; }
;     __device__ __forceinline__ const char* pa(const Gemm& g, const Unit& u, size_t tstep) const { return (const char*)g.A + (size_t)u.seg * astride + (size_t)u.pm * tstep; }
;     __device__ __forceinline__ const char* pb(const Gemm& g, const Unit& u, size_t tstep) const { return (const char*)g.Bt + (size_t)u.seg * bstride + (size_t)u.pn * tstep; }
; #define PG8_STAGE(bufoff, gbase, voff) do { _Pragma("unroll") for (int _i = 0; _i < 2; ++_i) \
;         __builtin_amdgcn_global_load_lds((const unsigned*)((const char*)(gbase) + (voff)[_i]), (PG8_LAS unsigned*)(lds + (bufoff) + ldsw + _i * 8192), 16, 0, 0); } while (0)
; #define PG8_WAIT_V(n) asm volatile("s_waitcnt vmcnt(" #n ")" ::: "memory")
; #define PG8_WAIT_L(n) asm volatile("s_waitcnt lgkmcnt(" #n ")" ::: "memory")
; #define PG8_BAR __builtin_amdgcn_s_barrier()
;     ...
;         const char* nA = has_next ? S.pa(g, nxt, tstepA) : cA; const char* nB = has_next ? S.pb(g, nxt, tstepB) : cB;
;         for (int t = 0; t < nt; t += 2) {
;             const bool last = (t == nt - 2);
;             const char* a1 = cA + (size_t)(t + 1) * kstep;
;             const char* a2 = last ? nA : cA + (size_t)(t + 2) * kstep; const char* b2 = last ? nB : cB + (size_t)(t + 2) * kstep;
;             const char* a3 = a2 + kstep; const char* b3 = b2 + kstep;
;             if (last && has_next) S.a_ready(nxt);
;             if constexpr (SP2) {
;             PG8_LDB(B0, 0, 0); PG8_LDB(B1, 0, 1); PG8_SCHED; PG8_LDA(At, 0, 0); PG8_STAGE(PG8_SA(1, 1), a1 + hstepA, voffA);
;             PG8_WAIT_V(8); PG8_WAIT_L(0); PG8_BAR; PG8_MMA(0, 0, At, B0); PG8_MMA(0, 1, At, B1); PG8_BAR; PG8_SCHED;
;             PG8_LDA(At, 0, 1); PG8_STAGE(PG8_SB(0, 0), b2, voffB); PG8_STAGE(PG8_SB(0, 1), b2 + hstepB, voffB); PG8_STAGE(PG8_SA(0, 0), a2, voffA);
;             PG8_WAIT_V(8); PG8_WAIT_L(0); PG8_BAR; PG8_MMA(1, 0, At, B0); PG8_MMA(1, 1, At, B1); PG8_BAR; PG8_SCHED;
.LBB0_607:
	s_ashr_i32 s37, s36, 31
	s_lshl_b64 s[40:41], s[36:37], 20
	s_add_u32 s40, s8, s40
	s_addc_u32 s41, s10, s41
	s_and_b64 s[42:43], s[38:39], exec
	s_cselect_b32 s37, s41, s51
	s_cselect_b32 s58, s40, s50
	s_ashr_i32 s31, s30, 31
	s_lshl_b64 s[42:43], s[30:31], 20
	s_add_u32 s42, s9, s42
	s_addc_u32 s43, s76, s43
	s_and_b64 s[54:55], s[38:39], exec
	s_cselect_b32 s31, s43, s53
	s_cselect_b32 s59, s42, s52
	s_add_u32 s50, s50, 0x80080
	s_addc_u32 s51, s51, 0
	s_add_u32 s60, s52, 0x100
	s_addc_u32 s61, s53, 0
	s_mov_b32 s62, -2
	s_add_u32 s52, s50, 0xfff80080
	s_addc_u32 s53, s51, -1
	s_add_i32 s63, 0, 0x10000
	s_cmp_eq_u32 s62, 28
	s_cselect_b32 s55, s37, s53
	s_cselect_b32 s54, s58, s52
	s_cselect_b32 s53, s31, s61
	s_cselect_b32 s52, s59, s60
	s_add_i32 s66, 0, 0x14000
	s_add_i32 m0, s12, 0xc000
	global_load_lds_dwordx4 v138, s[50:51]
	s_add_i32 m0, s12, 0xe000
	s_nop 0
	global_load_lds_dwordx4 v140, s[50:51]
	s_waitcnt vmcnt(8)
	s_waitcnt lgkmcnt(0)
	s_barrier
	v_mfma_f32_16x16x32_bf16 v[128:131], v[148:151], v[202:205], 0
	v_mfma_f32_16x16x32_bf16 v[124:127], v[156:159], v[202:205], 0
	v_mfma_f32_16x16x32_bf16 v[112:115], v[148:151], v[210:213], 0
	v_mfma_f32_16x16x32_bf16 v[108:111], v[156:159], v[210:213], 0
	v_mfma_f32_16x16x32_bf16 v[96:99], v[148:151], v[218:221], 0
	v_mfma_f32_16x16x32_bf16 v[92:95], v[156:159], v[218:221], 0
	v_mfma_f32_16x16x32_bf16 v[80:83], v[148:151], v[234:237], 0
	v_mfma_f32_16x16x32_bf16 v[76:79], v[156:159], v[234:237], 0
	v_mfma_f32_16x16x32_bf16 v[128:131], v[152:155], v[206:209], v[128:131]
	v_mfma_f32_16x16x32_bf16 v[124:127], v[160:163], v[206:209], v[124:127]
	v_mfma_f32_16x16x32_bf16 v[112:115], v[152:155], v[214:217], v[112:115]
	v_mfma_f32_16x16x32_bf16 v[108:111], v[160:163], v[214:217], v[108:111]
	v_mfma_f32_16x16x32_bf16 v[96:99], v[152:155], v[222:225], v[96:99]
	v_mfma_f32_16x16x32_bf16 v[92:95], v[160:163], v[222:225], v[92:95]
	v_mfma_f32_16x16x32_bf16 v[80:83], v[152:155], v[238:241], v[80:83]
	v_mfma_f32_16x16x32_bf16 v[76:79], v[160:163], v[238:241], v[76:79]
	v_mfma_f32_16x16x32_bf16 v[120:123], v[186:189], v[202:205], 0
	v_mfma_f32_16x16x32_bf16 v[116:119], v[194:197], v[202:205], 0
	v_mfma_f32_16x16x32_bf16 v[104:107], v[186:189], v[210:213], 0
	v_mfma_f32_16x16x32_bf16 v[100:103], v[194:197], v[210:213], 0
	v_mfma_f32_16x16x32_bf16 v[88:91], v[186:189], v[218:221], 0
	v_mfma_f32_16x16x32_bf16 v[84:87], v[194:197], v[218:221], 0
	v_mfma_f32_16x16x32_bf16 v[72:75], v[186:189], v[234:237], 0
	v_mfma_f32_16x16x32_bf16 v[68:71], v[194:197], v[234:237], 0
	v_mfma_f32_16x16x32_bf16 v[120:123], v[190:193], v[206:209], v[120:123]
	v_mfma_f32_16x16x32_bf16 v[116:119], v[198:201], v[206:209], v[116:119]
	v_mfma_f32_16x16x32_bf16 v[104:107], v[190:193], v[214:217], v[104:107]
	v_mfma_f32_16x16x32_bf16 v[100:103], v[198:201], v[214:217], v[100:103]
	v_mfma_f32_16x16x32_bf16 v[88:91], v[190:193], v[222:225], v[88:91]
	v_mfma_f32_16x16x32_bf16 v[84:87], v[198:201], v[222:225], v[84:87]
	v_mfma_f32_16x16x32_bf16 v[72:75], v[190:193], v[238:241], v[72:75]
	v_mfma_f32_16x16x32_bf16 v[68:71], v[198:201], v[238:241], v[68:71]
	s_barrier
	s_add_i32 s63, s63, s6
	s_mov_b32 m0, s63
	ds_read_b128 v[202:205], v147 offset:16384
	ds_read_b128 v[206:209], v147 offset:17408
	ds_read_b128 v[210:213], v147 offset:18432
	ds_read_b128 v[214:217], v147 offset:19456
	ds_read_b128 v[218:221], v147 offset:20480
	ds_read_b128 v[222:225], v147 offset:21504
	ds_read_b128 v[234:237], v147 offset:22528
	ds_read_b128 v[238:241], v147 offset:23552
	global_load_lds_dwordx4 v34, s[52:53]
	s_add_i32 m0, s63, 0x2000
	s_add_u32 s64, s52, 0x80000
	s_addc_u32 s65, s53, 0
	s_add_i32 s63, s66, s6
	global_load_lds_dwordx4 v132, s[52:53]
	s_mov_b32 m0, s63
	s_add_u32 s98, s54, 0x80
	s_addc_u32 s99, s55, 0
	global_load_lds_dwordx4 v34, s[64:65]
	s_add_i32 m0, s63, 0x2000
	s_nop 0
	global_load_lds_dwordx4 v132, s[64:65]
	s_mov_b32 m0, s12
	s_nop 0
	global_load_lds_dwordx4 v136, s[54:55]
	s_mov_b32 m0, s13
	s_nop 0
	global_load_lds_dwordx4 v134, s[54:55]
	s_waitcnt vmcnt(8)
	s_waitcnt lgkmcnt(0)
	s_barrier
	v_mfma_f32_16x16x32_bf16 v[64:67], v[148:151], v[202:205], 0
	v_mfma_f32_16x16x32_bf16 v[60:63], v[156:159], v[202:205], 0
	v_mfma_f32_16x16x32_bf16 v[48:51], v[148:151], v[210:213], 0
	v_mfma_f32_16x16x32_bf16 v[44:47], v[156:159], v[210:213], 0
	v_mfma_f32_16x16x32_bf16 v[30:33], v[148:151], v[218:221], 0
	v_mfma_f32_16x16x32_bf16 v[26:29], v[156:159], v[218:221], 0
	v_mfma_f32_16x16x32_bf16 v[14:17], v[148:151], v[234:237], 0
	v_mfma_f32_16x16x32_bf16 v[10:13], v[156:159], v[234:237], 0
	v_mfma_f32_16x16x32_bf16 v[64:67], v[152:155], v[206:209], v[64:67]
	v_mfma_f32_16x16x32_bf16 v[60:63], v[160:163], v[206:209], v[60:63]
	v_mfma_f32_16x16x32_bf16 v[48:51], v[152:155], v[214:217], v[48:51]
	v_mfma_f32_16x16x32_bf16 v[44:47], v[160:163], v[214:217], v[44:47]
	v_mfma_f32_16x16x32_bf16 v[30:33], v[152:155], v[222:225], v[30:33]
	v_mfma_f32_16x16x32_bf16 v[26:29], v[160:163], v[222:225], v[26:29]
	v_mfma_f32_16x16x32_bf16 v[14:17], v[152:155], v[238:241], v[14:17]
	v_mfma_f32_16x16x32_bf16 v[10:13], v[160:163], v[238:241], v[10:13]
	v_mfma_f32_16x16x32_bf16 v[56:59], v[186:189], v[202:205], 0
	v_mfma_f32_16x16x32_bf16 v[52:55], v[194:197], v[202:205], 0
	v_mfma_f32_16x16x32_bf16 v[40:43], v[186:189], v[210:213], 0
	v_mfma_f32_16x16x32_bf16 v[36:39], v[194:197], v[210:213], 0
	v_mfma_f32_16x16x32_bf16 v[22:25], v[186:189], v[218:221], 0
	v_mfma_f32_16x16x32_bf16 v[18:21], v[194:197], v[218:221], 0
	v_mfma_f32_16x16x32_bf16 v[6:9], v[186:189], v[234:237], 0
	v_mfma_f32_16x16x32_bf16 v[2:5], v[194:197], v[234:237], 0
	v_mfma_f32_16x16x32_bf16 v[56:59], v[190:193], v[206:209], v[56:59]
	v_mfma_f32_16x16x32_bf16 v[52:55], v[198:201], v[206:209], v[52:55]
	v_mfma_f32_16x16x32_bf16 v[40:43], v[190:193], v[214:217], v[40:43]
	v_mfma_f32_16x16x32_bf16 v[36:39], v[198:201], v[214:217], v[36:39]
	v_mfma_f32_16x16x32_bf16 v[22:25], v[190:193], v[222:225], v[22:25]
	v_mfma_f32_16x16x32_bf16 v[18:21], v[198:201], v[222:225], v[18:21]
	v_mfma_f32_16x16x32_bf16 v[6:9], v[190:193], v[238:241], v[6:9]
	v_mfma_f32_16x16x32_bf16 v[2:5], v[198:201], v[238:241], v[2:5]
	s_barrier
	s_branch .Lpeel_mid_608
	.p2align	6

;     __device__ __forceinline__ bool next(int i, Unit& u) const { const int ti = i / 3, sg = i - 3 * ti; if (!StaticOrder::next(ti, u)) return false; u.seg = sg; return true; }
;     __host__ __device__ __forceinline__ bool next(int i, Unit& u) const {
;         const long L = (long)i * G + c; if (L >= nwg) return false;
;         int wgid = (int)L; { const int q = nwg / NXCD, r = nwg % NXCD, xcd = wgid % NXCD, off = wgid / NXCD; wgid = (xcd < r ? xcd * (q + 1) : r * (q + 1) + (xcd - r) * q) + off; }
;         const int nig = WGM * nN, gid = wgid / nig, fm = gid * WGM, gsz = (nM - fm) < WGM ? (nM - fm) : WGM;
.LBB0_683:
	v_add_u32_e32 v163, 0x10000, v143
	ds_read_b128 v[146:149], v163
	ds_read_b128 v[150:153], v163 offset:1024
	ds_read_b128 v[154:157], v163 offset:2048
	ds_read_b128 v[158:161], v163 offset:3072
	ds_read_b128 v[186:189], v163 offset:16384
	ds_read_b128 v[190:193], v163 offset:17408
	ds_read_b128 v[194:197], v163 offset:18432
	ds_read_b128 v[198:201], v163 offset:19456
	ds_read_b128 v[202:205], v145
	ds_read_b128 v[206:209], v145 offset:1024
	ds_read_b128 v[210:213], v145 offset:2048
	ds_read_b128 v[214:217], v145 offset:3072
	ds_read_b128 v[218:221], v145 offset:4096
	ds_read_b128 v[222:225], v145 offset:5120
	ds_read_b128 v[234:237], v145 offset:6144
	ds_read_b128 v[238:241], v145 offset:7168
	s_add_i32 s60, s60, 1
	s_mul_i32 s36, s60, s58
	s_mul_hi_u32 s37, s60, s24
	s_add_i32 s37, s37, s36
	s_mul_i32 s36, s60, s24
	s_add_u32 s36, s36, s13
	s_addc_u32 s37, s37, s6
	v_cmp_gt_i64_e32 vcc, s[36:37], v[170:171]
	v_cmp_lt_i64_e64 s[40:41], s[36:37], v[168:169]
	s_cbranch_vccnz .LBB0_689
	s_ashr_i32 s37, s36, 31
	s_lshr_b32 s37, s37, 29
	s_add_i32 s38, s36, s37
	s_and_b32 s37, s38, -8
	s_sub_i32 s39, s36, s37
	s_cmp_gt_i32 s39, -1
	s_mov_b64 s[36:37], -1
	s_cbranch_scc0 .LBB0_686
	s_lshl_b32 s50, s39, 6
	s_mov_b64 s[36:37], 0

;     __device__ __forceinline__ const char* pa(const Gemm& g, const Unit& u, size_t tstep) const { return (const char*)g.A + (size_t)u.pm * tstep; }
;     __device__ __forceinline__ const char* pb(const Gemm& g, const Unit& u, size_t tstep) const { return (const char*)g.Bt + (size_t)u.pn * tstep; }
;     __device__ __forceinline__ const char* pa(const Gemm& g, const Unit& u, size_t tstep) const { return (const char*)g.A + (size_t)(u.pn >> 1) * 512 + (size_t)u.pm * tstep; }
;     __device__ __forceinline__ const char* pa(const Gemm& g, const Unit& u, size_t tstep) const { return (const char*)g.A + (size_t)u.seg * astride + (size_t)u.pm * tstep; }
;     __device__ __forceinline__ const char* pb(const Gemm& g, const Unit& u, size_t tstep) const { return (const char*)g.Bt + (size_t)u.seg * bstride + (size_t)u.pn * tstep; }
; #define PG8_STAGE(bufoff, gbase, voff) do { _Pragma("unroll") for (int _i = 0; _i < 2; ++_i) \
;         __builtin_amdgcn_global_load_lds((const unsigned*)((const char*)(gbase) + (voff)[_i]), (PG8_LAS unsigned*)(lds + (bufoff) + ldsw + _i * 8192), 16, 0, 0); } while (0)
; #define PG8_WAIT_V(n) asm volatile("s_waitcnt vmcnt(" #n ")" ::: "memory")
; #define PG8_WAIT_L(n) asm volatile("s_waitcnt lgkmcnt(" #n ")" ::: "memory")
; #define PG8_BAR __builtin_amdgcn_s_barrier()
;     ...
;         const char* nA = has_next ? S.pa(g, nxt, tstepA) : cA; const char* nB = has_next ? S.pb(g, nxt, tstepB) : cB;
;         for (int t = 0; t < nt; t += 2) {
;             const bool last = (t == nt - 2);
;             const char* a1 = cA + (size_t)(t + 1) * kstep;
;             const char* a2 = last ? nA : cA + (size_t)(t + 2) * kstep; const char* b2 = last ? nB : cB + (size_t)(t + 2) * kstep;
;             const char* a3 = a2 + kstep; const char* b3 = b2 + kstep;
;             if (last && has_next) S.a_ready(nxt);
;             if constexpr (SP2) {
;             PG8_LDB(B0, 0, 0); PG8_LDB(B1, 0, 1); PG8_SCHED; PG8_LDA(At, 0, 0); PG8_STAGE(PG8_SA(1, 1), a1 + hstepA, voffA);
;             PG8_WAIT_V(8); PG8_WAIT_L(0); PG8_BAR; PG8_MMA(0, 0, At, B0); PG8_MMA(0, 1, At, B1); PG8_BAR; PG8_SCHED;
;             PG8_LDA(At, 0, 1); PG8_STAGE(PG8_SB(0, 0), b2, voffB); PG8_STAGE(PG8_SB(0, 1), b2 + hstepB, voffB); PG8_STAGE(PG8_SA(0, 0), a2, voffA);
;             PG8_WAIT_V(8); PG8_WAIT_L(0); PG8_BAR; PG8_MMA(1, 0, At, B0); PG8_MMA(1, 1, At, B1); PG8_BAR; PG8_SCHED;
.LBB0_693:
	s_add_u32 s64, s44, 0x100
	s_addc_u32 s65, s45, 0
	s_mov_b32 s66, -2
	s_add_u32 s44, s42, 0x100
	s_addc_u32 s45, s43, 0
	s_add_i32 s67, 0, 0x10000
	s_cmpk_eq_i32 s66, 0x54
	s_cselect_b32 s53, s37, s45
	s_cselect_b32 s52, s36, s44
	s_cselect_b32 s51, s41, s65
	s_cselect_b32 s50, s40, s64
	s_add_i32 s68, 0, 0x14000
	s_add_i32 m0, s34, 0xc000
	global_load_lds_dwordx4 v138, s[42:43]
	s_add_i32 m0, s34, 0xe000
	s_nop 0
	global_load_lds_dwordx4 v140, s[42:43]
	s_waitcnt vmcnt(8)
	s_waitcnt lgkmcnt(0)
	s_barrier
	v_mfma_f32_16x16x32_bf16 v[128:131], v[146:149], v[202:205], 0
	v_mfma_f32_16x16x32_bf16 v[124:127], v[154:157], v[202:205], 0
	v_mfma_f32_16x16x32_bf16 v[120:123], v[146:149], v[210:213], 0
	v_mfma_f32_16x16x32_bf16 v[116:119], v[154:157], v[210:213], 0
	v_mfma_f32_16x16x32_bf16 v[104:107], v[146:149], v[218:221], 0
	v_mfma_f32_16x16x32_bf16 v[100:103], v[154:157], v[218:221], 0
	v_mfma_f32_16x16x32_bf16 v[88:91], v[146:149], v[234:237], 0
	v_mfma_f32_16x16x32_bf16 v[84:87], v[154:157], v[234:237], 0
	v_mfma_f32_16x16x32_bf16 v[128:131], v[150:153], v[206:209], v[128:131]
	v_mfma_f32_16x16x32_bf16 v[124:127], v[158:161], v[206:209], v[124:127]
	v_mfma_f32_16x16x32_bf16 v[120:123], v[150:153], v[214:217], v[120:123]
	v_mfma_f32_16x16x32_bf16 v[116:119], v[158:161], v[214:217], v[116:119]
	v_mfma_f32_16x16x32_bf16 v[104:107], v[150:153], v[222:225], v[104:107]
	v_mfma_f32_16x16x32_bf16 v[100:103], v[158:161], v[222:225], v[100:103]
	v_mfma_f32_16x16x32_bf16 v[88:91], v[150:153], v[238:241], v[88:91]
	v_mfma_f32_16x16x32_bf16 v[84:87], v[158:161], v[238:241], v[84:87]
	v_mfma_f32_16x16x32_bf16 v[112:115], v[186:189], v[202:205], 0
	v_mfma_f32_16x16x32_bf16 v[108:111], v[194:197], v[202:205], 0
	v_mfma_f32_16x16x32_bf16 v[96:99], v[186:189], v[210:213], 0
	v_mfma_f32_16x16x32_bf16 v[92:95], v[194:197], v[210:213], 0
	v_mfma_f32_16x16x32_bf16 v[80:83], v[186:189], v[218:221], 0
	v_mfma_f32_16x16x32_bf16 v[76:79], v[194:197], v[218:221], 0
	v_mfma_f32_16x16x32_bf16 v[72:75], v[186:189], v[234:237], 0
	v_mfma_f32_16x16x32_bf16 v[68:71], v[194:197], v[234:237], 0
	v_mfma_f32_16x16x32_bf16 v[112:115], v[190:193], v[206:209], v[112:115]
	v_mfma_f32_16x16x32_bf16 v[108:111], v[198:201], v[206:209], v[108:111]
	v_mfma_f32_16x16x32_bf16 v[96:99], v[190:193], v[214:217], v[96:99]
	v_mfma_f32_16x16x32_bf16 v[92:95], v[198:201], v[214:217], v[92:95]
	v_mfma_f32_16x16x32_bf16 v[80:83], v[190:193], v[222:225], v[80:83]
	v_mfma_f32_16x16x32_bf16 v[76:79], v[198:201], v[222:225], v[76:79]
	v_mfma_f32_16x16x32_bf16 v[72:75], v[190:193], v[238:241], v[72:75]
	v_mfma_f32_16x16x32_bf16 v[68:71], v[198:201], v[238:241], v[68:71]
	s_barrier
	s_add_i32 s42, s67, s15
	s_mov_b32 m0, s42
	ds_read_b128 v[202:205], v145 offset:16384
	ds_read_b128 v[206:209], v145 offset:17408
	ds_read_b128 v[210:213], v145 offset:18432
	ds_read_b128 v[214:217], v145 offset:19456
	ds_read_b128 v[218:221], v145 offset:20480
	ds_read_b128 v[222:225], v145 offset:21504
	ds_read_b128 v[234:237], v145 offset:22528
	ds_read_b128 v[238:241], v145 offset:23552
	global_load_lds_dwordx4 v34, s[50:51]
	s_add_i32 m0, s42, 0x2000
	s_add_u32 s42, s50, 0x160000
	s_addc_u32 s43, s51, 0
	s_add_u32 s98, s50, 0x80
	s_addc_u32 s99, s51, 0
	s_add_i32 s67, s68, s15
	global_load_lds_dwordx4 v136, s[50:51]
	s_mov_b32 m0, s67
	s_nop 0
	global_load_lds_dwordx4 v34, s[42:43]
	s_add_i32 m0, s67, 0x2000
	s_nop 0
	global_load_lds_dwordx4 v136, s[42:43]
	s_mov_b32 m0, s34
	s_nop 0
	global_load_lds_dwordx4 v132, s[52:53]
	s_mov_b32 m0, s35
	s_nop 0
	global_load_lds_dwordx4 v134, s[52:53]
	s_waitcnt vmcnt(8)
	s_waitcnt lgkmcnt(0)
	s_barrier
	v_mfma_f32_16x16x32_bf16 v[64:67], v[146:149], v[202:205], 0
	v_mfma_f32_16x16x32_bf16 v[60:63], v[154:157], v[202:205], 0
	v_mfma_f32_16x16x32_bf16 v[56:59], v[146:149], v[210:213], 0
	v_mfma_f32_16x16x32_bf16 v[52:55], v[154:157], v[210:213], 0
	v_mfma_f32_16x16x32_bf16 v[40:43], v[146:149], v[218:221], 0
	v_mfma_f32_16x16x32_bf16 v[36:39], v[154:157], v[218:221], 0
	v_mfma_f32_16x16x32_bf16 v[22:25], v[146:149], v[234:237], 0
	v_mfma_f32_16x16x32_bf16 v[18:21], v[154:157], v[234:237], 0
	v_mfma_f32_16x16x32_bf16 v[64:67], v[150:153], v[206:209], v[64:67]
	v_mfma_f32_16x16x32_bf16 v[60:63], v[158:161], v[206:209], v[60:63]
	v_mfma_f32_16x16x32_bf16 v[56:59], v[150:153], v[214:217], v[56:59]
	v_mfma_f32_16x16x32_bf16 v[52:55], v[158:161], v[214:217], v[52:55]
	v_mfma_f32_16x16x32_bf16 v[40:43], v[150:153], v[222:225], v[40:43]
	v_mfma_f32_16x16x32_bf16 v[36:39], v[158:161], v[222:225], v[36:39]
	v_mfma_f32_16x16x32_bf16 v[22:25], v[150:153], v[238:241], v[22:25]
	v_mfma_f32_16x16x32_bf16 v[18:21], v[158:161], v[238:241], v[18:21]
	v_mfma_f32_16x16x32_bf16 v[48:51], v[186:189], v[202:205], 0
	v_mfma_f32_16x16x32_bf16 v[44:47], v[194:197], v[202:205], 0
	v_mfma_f32_16x16x32_bf16 v[30:33], v[186:189], v[210:213], 0
	v_mfma_f32_16x16x32_bf16 v[26:29], v[194:197], v[210:213], 0
	v_mfma_f32_16x16x32_bf16 v[14:17], v[186:189], v[218:221], 0
	v_mfma_f32_16x16x32_bf16 v[10:13], v[194:197], v[218:221], 0
	v_mfma_f32_16x16x32_bf16 v[6:9], v[186:189], v[234:237], 0
	v_mfma_f32_16x16x32_bf16 v[2:5], v[194:197], v[234:237], 0
	v_mfma_f32_16x16x32_bf16 v[48:51], v[190:193], v[206:209], v[48:51]
	v_mfma_f32_16x16x32_bf16 v[44:47], v[198:201], v[206:209], v[44:47]
	v_mfma_f32_16x16x32_bf16 v[30:33], v[190:193], v[214:217], v[30:33]
	v_mfma_f32_16x16x32_bf16 v[26:29], v[198:201], v[214:217], v[26:29]
	v_mfma_f32_16x16x32_bf16 v[14:17], v[190:193], v[222:225], v[14:17]
	v_mfma_f32_16x16x32_bf16 v[10:13], v[198:201], v[222:225], v[10:13]
	v_mfma_f32_16x16x32_bf16 v[6:9], v[190:193], v[238:241], v[6:9]
	v_mfma_f32_16x16x32_bf16 v[2:5], v[198:201], v[238:241], v[2:5]
	s_barrier
	s_branch .Lpeel_mid_694
	.p2align	6

;     __device__ __forceinline__ bool next(int i, Unit& u) const { const int ti = i / 3, sg = i - 3 * ti; if (!StaticOrder::next(ti, u)) return false; u.seg = sg; return true; }
;     __host__ __device__ __forceinline__ bool next(int i, Unit& u) const {
;         const long L = (long)i * G + c; if (L >= nwg) return false;
;         int wgid = (int)L; { const int q = nwg / NXCD, r = nwg % NXCD, xcd = wgid % NXCD, off = wgid / NXCD; wgid = (xcd < r ? xcd * (q + 1) : r * (q + 1) + (xcd - r) * q) + off; }
;         const int nig = WGM * nN, gid = wgid / nig, fm = gid * WGM, gsz = (nM - fm) < WGM ? (nM - fm) : WGM;
.LBB0_715:
	v_add_u32_e32 v250, 0x10000, v209
	ds_read_b128 v[26:29], v250
	ds_read_b128 v[30:33], v250 offset:1024
	ds_read_b128 v[18:21], v250 offset:2048
	ds_read_b128 v[22:25], v250 offset:3072
	ds_read_b128 v[10:13], v250 offset:16384
	ds_read_b128 v[14:17], v250 offset:17408
	ds_read_b128 v[2:5], v250 offset:18432
	ds_read_b128 v[6:9], v250 offset:19456
	ds_read_b128 v[200:203], v211
	ds_read_b128 v[204:207], v211 offset:1024
	ds_read_b128 v[212:215], v211 offset:2048
	ds_read_b128 v[216:219], v211 offset:3072
	ds_read_b128 v[220:223], v211 offset:4096
	ds_read_b128 v[224:227], v211 offset:5120
	ds_read_b128 v[234:237], v211 offset:6144
	ds_read_b128 v[238:241], v211 offset:7168
	s_add_i32 s58, s58, 1
	s_mul_i32 s30, s58, s57
	s_mul_hi_u32 s31, s58, s24
	s_add_i32 s31, s31, s30
	s_mul_i32 s30, s58, s24
	s_add_u32 s30, s30, s13
	s_addc_u32 s31, s31, s6
	v_cmp_gt_i64_e32 vcc, s[30:31], v[170:171]
	v_cmp_lt_i64_e64 s[40:41], s[30:31], v[168:169]
	s_cbranch_vccnz .LBB0_721
	s_ashr_i32 s31, s30, 31
	s_lshr_b32 s31, s31, 29
	s_add_i32 s36, s30, s31
	s_and_b32 s31, s36, -8
	s_sub_i32 s37, s30, s31
	s_cmp_gt_i32 s37, -1
	s_mov_b64 s[30:31], -1
	s_cbranch_scc0 .LBB0_718
	s_lshl_b32 s38, s37, 6
	s_mov_b64 s[30:31], 0

;     __device__ __forceinline__ const char* pa(const Gemm& g, const Unit& u, size_t tstep) const { return (const char*)g.A + (size_t)u.pm * tstep; }
;     __device__ __forceinline__ const char* pb(const Gemm& g, const Unit& u, size_t tstep) const { return (const char*)g.Bt + (size_t)u.pn * tstep; }
;     __device__ __forceinline__ const char* pa(const Gemm& g, const Unit& u, size_t tstep) const { return (const char*)g.A + (size_t)(u.pn >> 1) * 512 + (size_t)u.pm * tstep; }
;     __device__ __forceinline__ bool next(int i, Unit& u) const { const int ti = i / 3, sg = i - 3 * ti; if (!StaticOrder::next(ti, u)) return false; u.seg = sg; return true; }
;     __device__ __forceinline__ const char* pa(const Gemm& g, const Unit& u, size_t tstep) const { return (const char*)g.A + (size_t)u.seg * astride + (size_t)u.pm * tstep; }
;     __device__ __forceinline__ const char* pb(const Gemm& g, const Unit& u, size_t tstep) const { return (const char*)g.Bt + (size_t)u.seg * bstride + (size_t)u.pn * tstep; }
;     __host__ __device__ __forceinline__ bool next(int i, Unit& u) const {
;     ...
;         int wgid = (int)L; { const int q = nwg / NXCD, r = nwg % NXCD, xcd = wgid % NXCD, off = wgid / NXCD; wgid = (xcd < r ? xcd * (q + 1) : r * (q + 1) + (xcd - r) * q) + off; }
;         const int nig = WGM * nN, gid = wgid / nig, fm = gid * WGM, gsz = (nM - fm) < WGM ? (nM - fm) : WGM;
;         u.pm = fm + ((wgid % nig) % gsz); u.pn = (wgid % nig) / gsz; u.seg = 0; return true;
;     }
;     ...
;         const bool has_next = S.next(ui + 1, nxt);
;         const char* nA = has_next ? S.pa(g, nxt, tstepA) : cA; const char* nB = has_next ? S.pb(g, nxt, tstepB) : cB;
.LBB0_720:
	s_ashr_i32 s30, s36, 3
	s_add_i32 s30, s38, s30
	s_ashr_i32 s31, s30, 31
	s_lshr_b32 s31, s31, 26
	s_add_i32 s31, s30, s31
	s_ashr_i32 s36, s31, 6
	s_lshl_b32 s36, s36, 3
	s_sub_i32 s37, 64, s36
	s_min_i32 s37, s37, 8
	s_abs_i32 s38, s37
	v_cvt_f32_u32_e32 v249, s38
	s_sub_i32 s50, 0, s38
	s_andn2_b32 s31, s31, 63
	s_sub_i32 s30, s30, s31
	v_rcp_iflag_f32_e32 v249, v249
	s_abs_i32 s31, s30
	s_xor_b32 s39, s30, s37
	s_ashr_i32 s39, s39, 31
	v_mul_f32_e32 v249, 0x4f7ffffe, v249
	v_cvt_u32_f32_e32 v249, v249
	s_nop 0
	v_readfirstlane_b32 s51, v249
	s_mul_i32 s50, s50, s51
	s_mul_hi_u32 s50, s51, s50
	s_add_i32 s51, s51, s50
	s_mul_hi_u32 s50, s31, s51
	s_mul_i32 s51, s50, s38
	s_sub_i32 s31, s31, s51
	s_add_i32 s59, s50, 1
	s_sub_i32 s51, s31, s38
	s_cmp_ge_u32 s31, s38
	s_cselect_b32 s50, s59, s50
	s_cselect_b32 s31, s51, s31
	s_add_i32 s51, s50, 1
	s_cmp_ge_u32 s31, s38
	s_cselect_b32 s31, s51, s50
	s_xor_b32 s31, s31, s39
	s_sub_i32 s59, s31, s39
	s_mul_i32 s31, s59, s37
	s_sub_i32 s30, s30, s31
	s_add_i32 s60, s36, s30
.LBB0_721:
	s_nop 0
	v_cndmask_b32_e64 v249, 0, 1, s[40:41]
	v_cmp_ne_u32_e64 s[38:39], 1, v249
	s_andn2_b64 vcc, exec, s[40:41]
	s_mov_b64 s[30:31], s[42:43]
	s_cbranch_vccnz .LBB0_723
	s_mul_i32 s30, s60, 0x160000
	s_mul_hi_i32 s31, s60, 0x160000
	s_add_u32 s30, s9, s30
	s_addc_u32 s31, s10, s31

;     __device__ __forceinline__ const char* pa(const Gemm& g, const Unit& u, size_t tstep) const { return (const char*)g.A + (size_t)u.pm * tstep; }
;     __device__ __forceinline__ const char* pb(const Gemm& g, const Unit& u, size_t tstep) const { return (const char*)g.Bt + (size_t)u.pn * tstep; }
;     __device__ __forceinline__ const char* pa(const Gemm& g, const Unit& u, size_t tstep) const { return (const char*)g.A + (size_t)(u.pn >> 1) * 512 + (size_t)u.pm * tstep; }
;     __device__ __forceinline__ const char* pa(const Gemm& g, const Unit& u, size_t tstep) const { return (const char*)g.A + (size_t)u.seg * astride + (size_t)u.pm * tstep; }
;     __device__ __forceinline__ const char* pb(const Gemm& g, const Unit& u, size_t tstep) const { return (const char*)g.Bt + (size_t)u.seg * bstride + (size_t)u.pn * tstep; }
; #define PG8_STAGE(bufoff, gbase, voff) do { _Pragma("unroll") for (int _i = 0; _i < 2; ++_i) \
;         __builtin_amdgcn_global_load_lds((const unsigned*)((const char*)(gbase) + (voff)[_i]), (PG8_LAS unsigned*)(lds + (bufoff) + ldsw + _i * 8192), 16, 0, 0); } while (0)
; #define PG8_WAIT_V(n) asm volatile("s_waitcnt vmcnt(" #n ")" ::: "memory")
; #define PG8_WAIT_L(n) asm volatile("s_waitcnt lgkmcnt(" #n ")" ::: "memory")
; #define PG8_BAR __builtin_amdgcn_s_barrier()
;     ...
;         const char* nA = has_next ? S.pa(g, nxt, tstepA) : cA; const char* nB = has_next ? S.pb(g, nxt, tstepB) : cB;
;         for (int t = 0; t < nt; t += 2) {
;             const bool last = (t == nt - 2);
;             const char* a1 = cA + (size_t)(t + 1) * kstep;
;             const char* a2 = last ? nA : cA + (size_t)(t + 2) * kstep; const char* b2 = last ? nB : cB + (size_t)(t + 2) * kstep;
;             const char* a3 = a2 + kstep; const char* b3 = b2 + kstep;
;             if (last && has_next) S.a_ready(nxt);
;             if constexpr (SP2) {
;             PG8_LDB(B0, 0, 0); PG8_LDB(B1, 0, 1); PG8_SCHED; PG8_LDA(At, 0, 0); PG8_STAGE(PG8_SA(1, 1), a1 + hstepA, voffA);
;             PG8_WAIT_V(8); PG8_WAIT_L(0); PG8_BAR; PG8_MMA(0, 0, At, B0); PG8_MMA(0, 1, At, B1); PG8_BAR; PG8_SCHED;
;             PG8_LDA(At, 0, 1); PG8_STAGE(PG8_SB(0, 0), b2, voffB); PG8_STAGE(PG8_SB(0, 1), b2 + hstepB, voffB); PG8_STAGE(PG8_SA(0, 0), a2, voffA);
;             PG8_WAIT_V(8); PG8_WAIT_L(0); PG8_BAR; PG8_MMA(1, 0, At, B0); PG8_MMA(1, 1, At, B1); PG8_BAR; PG8_SCHED;
.LBB0_725:
	s_add_u32 s61, s44, 0x100
	s_addc_u32 s62, s45, 0
	s_mov_b32 s63, -2
	s_add_u32 s40, s42, 0x100
	s_addc_u32 s41, s43, 0
	s_add_i32 s64, 0, 0x10000
	s_cmp_eq_u32 s63, 40
	s_cselect_b32 s51, s31, s41
	s_cselect_b32 s50, s30, s40
	s_cselect_b32 s45, s37, s62
	s_cselect_b32 s44, s36, s61
	s_add_i32 s65, 0, 0x14000
	s_add_i32 m0, s21, 0xc000
	global_load_lds_dwordx4 v196, s[42:43]
	s_add_i32 m0, s21, 0xe000
	s_nop 0
	global_load_lds_dwordx4 v198, s[42:43]
	s_waitcnt vmcnt(8)
	s_waitcnt lgkmcnt(0)
	s_barrier
	v_mfma_f32_16x16x128_f8f6f4 v[160:163], v[26:33], v[200:207], 0
	v_mfma_f32_16x16x128_f8f6f4 v[156:159], v[18:25], v[200:207], 0
	v_mfma_f32_16x16x128_f8f6f4 v[152:155], v[26:33], v[212:219], 0
	v_mfma_f32_16x16x128_f8f6f4 v[144:147], v[18:25], v[212:219], 0
	v_mfma_f32_16x16x128_f8f6f4 v[136:139], v[26:33], v[220:227], 0
	v_mfma_f32_16x16x128_f8f6f4 v[128:131], v[18:25], v[220:227], 0
	v_mfma_f32_16x16x128_f8f6f4 v[120:123], v[26:33], v[234:241], 0
	v_mfma_f32_16x16x128_f8f6f4 v[112:115], v[18:25], v[234:241], 0
	v_mfma_f32_16x16x128_f8f6f4 v[148:151], v[10:17], v[200:207], 0
	v_mfma_f32_16x16x128_f8f6f4 v[140:143], v[2:9], v[200:207], 0
	v_mfma_f32_16x16x128_f8f6f4 v[132:135], v[10:17], v[212:219], 0
	v_mfma_f32_16x16x128_f8f6f4 v[124:127], v[2:9], v[212:219], 0
	v_mfma_f32_16x16x128_f8f6f4 v[116:119], v[10:17], v[220:227], 0
	v_mfma_f32_16x16x128_f8f6f4 v[108:111], v[2:9], v[220:227], 0
	v_mfma_f32_16x16x128_f8f6f4 v[104:107], v[10:17], v[234:241], 0
	v_mfma_f32_16x16x128_f8f6f4 v[100:103], v[2:9], v[234:241], 0
	s_barrier
	s_add_i32 s42, s64, s15
	s_mov_b32 m0, s42
	ds_read_b128 v[212:215], v211 offset:16384
	ds_read_b128 v[216:219], v211 offset:17408
	ds_read_b128 v[220:223], v211 offset:18432
	ds_read_b128 v[224:227], v211 offset:19456
	ds_read_b128 v[234:237], v211 offset:20480
	ds_read_b128 v[238:241], v211 offset:21504
	ds_read_b128 v[242:245], v211 offset:22528
	ds_read_b128 v[246:249], v211 offset:23552
	global_load_lds_dwordx4 v34, s[44:45]
	s_add_i32 m0, s42, 0x2000
	s_add_u32 s42, s44, 0xb0000
	s_addc_u32 s43, s45, 0
	s_add_u32 s98, s44, 0x80
	s_addc_u32 s99, s45, 0
	s_add_i32 s64, s65, s15
	global_load_lds_dwordx4 v190, s[44:45]
	s_mov_b32 m0, s64
	s_nop 0
	global_load_lds_dwordx4 v34, s[42:43]
	s_add_i32 m0, s64, 0x2000
	s_nop 0
	global_load_lds_dwordx4 v190, s[42:43]
	s_mov_b32 m0, s21
	s_nop 0
	global_load_lds_dwordx4 v186, s[50:51]
	s_mov_b32 m0, s34
	s_nop 0
	global_load_lds_dwordx4 v188, s[50:51]
	s_waitcnt vmcnt(8)
	s_waitcnt lgkmcnt(0)
	s_barrier
	v_mfma_f32_16x16x128_f8f6f4 v[96:99], v[26:33], v[212:219], 0
	v_mfma_f32_16x16x128_f8f6f4 v[92:95], v[18:25], v[212:219], 0
	v_mfma_f32_16x16x128_f8f6f4 v[88:91], v[26:33], v[220:227], 0
	v_mfma_f32_16x16x128_f8f6f4 v[80:83], v[18:25], v[220:227], 0
	v_mfma_f32_16x16x128_f8f6f4 v[72:75], v[26:33], v[234:241], 0
	v_mfma_f32_16x16x128_f8f6f4 v[64:67], v[18:25], v[234:241], 0
	v_mfma_f32_16x16x128_f8f6f4 v[56:59], v[26:33], v[242:249], 0
	v_mfma_f32_16x16x128_f8f6f4 v[48:51], v[18:25], v[242:249], 0
	v_mfma_f32_16x16x128_f8f6f4 v[84:87], v[10:17], v[212:219], 0
	v_mfma_f32_16x16x128_f8f6f4 v[76:79], v[2:9], v[212:219], 0
	v_mfma_f32_16x16x128_f8f6f4 v[68:71], v[10:17], v[220:227], 0
	v_mfma_f32_16x16x128_f8f6f4 v[60:63], v[2:9], v[220:227], 0
	v_mfma_f32_16x16x128_f8f6f4 v[52:55], v[10:17], v[234:241], 0
	v_mfma_f32_16x16x128_f8f6f4 v[44:47], v[2:9], v[234:241], 0
	v_mfma_f32_16x16x128_f8f6f4 v[40:43], v[10:17], v[242:249], 0
	v_mfma_f32_16x16x128_f8f6f4 v[36:39], v[2:9], v[242:249], 0
	s_barrier
	s_branch .Lpeel_mid_726
	.p2align	6

;     __device__ __forceinline__ bool next(int i, Unit& u) const { const int ti = i / 3, sg = i - 3 * ti; if (!StaticOrder::next(ti, u)) return false; u.seg = sg; return true; }
;     __host__ __device__ __forceinline__ bool next(int i, Unit& u) const {
;         const long L = (long)i * G + c; if (L >= nwg) return false;
;         int wgid = (int)L; { const int q = nwg / NXCD, r = nwg % NXCD, xcd = wgid % NXCD, off = wgid / NXCD; wgid = (xcd < r ? xcd * (q + 1) : r * (q + 1) + (xcd - r) * q) + off; }
;         const int nig = WGM * nN, gid = wgid / nig, fm = gid * WGM, gsz = (nM - fm) < WGM ? (nM - fm) : WGM;
;         u.pm = fm + ((wgid % nig) % gsz); u.pn = (wgid % nig) / gsz; u.seg = 0; return true;
;     }
.LBB0_920:
	v_add_u32_e32 v226, 0x10000, v153
	ds_read_b128 v[132:135], v226
	ds_read_b128 v[136:139], v226 offset:1024
	ds_read_b128 v[156:159], v226 offset:2048
	ds_read_b128 v[160:163], v226 offset:3072
	ds_read_b128 v[186:189], v226 offset:16384
	ds_read_b128 v[190:193], v226 offset:17408
	ds_read_b128 v[194:197], v226 offset:18432
	ds_read_b128 v[198:201], v226 offset:19456
	ds_read_b128 v[202:205], v155
	ds_read_b128 v[206:209], v155 offset:1024
	ds_read_b128 v[210:213], v155 offset:2048
	ds_read_b128 v[214:217], v155 offset:3072
	ds_read_b128 v[218:221], v155 offset:4096
	ds_read_b128 v[222:225], v155 offset:5120
	ds_read_b128 v[234:237], v155 offset:6144
	ds_read_b128 v[238:241], v155 offset:7168
	s_add_i32 s75, s75, 1
	s_mul_i32 s6, s75, s67
	s_mul_hi_u32 s15, s75, s64
	s_add_i32 s15, s15, s6
	s_mul_i32 s6, s75, s64
	s_add_u32 s48, s6, s65
	s_addc_u32 s49, s15, s74
	v_cmp_gt_i64_e32 vcc, s[48:49], v[176:177]
	v_cmp_lt_i64_e64 s[38:39], s[48:49], v[174:175]
	s_cbranch_vccnz .LBB0_922
	s_ashr_i32 s6, s48, 31
	s_lshr_b32 s6, s6, 29
	s_add_i32 s6, s48, s6
	s_ashr_i32 s15, s6, 3
	s_and_b32 s6, s6, -8
	s_sub_i32 s6, s48, s6
	s_cmp_lt_i32 s6, 0
	s_movk_i32 s34, 0x121
	s_cselect_b32 s34, s34, 0x120
	s_mul_i32 s6, s6, s34
	s_add_i32 s6, s6, s15
	s_mul_hi_i32 s15, s6, 0x38e38e39
	s_lshr_b32 s34, s15, 31
	s_ashr_i32 s15, s15, 6
	s_add_i32 s15, s15, s34
	s_lshl_b32 s34, s15, 3
	s_sub_i32 s35, 64, s34
	s_min_i32 s35, s35, 8
	s_abs_i32 s36, s35
	v_cvt_f32_u32_e32 v2, s36
	s_sub_i32 s41, 0, s36
	s_mulk_i32 s15, 0x120
	s_sub_i32 s6, s6, s15
	v_rcp_iflag_f32_e32 v2, v2
	s_abs_i32 s15, s6
	s_xor_b32 s37, s6, s35
	s_ashr_i32 s37, s37, 31
	v_mul_f32_e32 v2, 0x4f7ffffe, v2
	v_cvt_u32_f32_e32 v2, v2
	s_nop 0
	v_readfirstlane_b32 s46, v2
	s_mul_i32 s41, s41, s46
	s_mul_hi_u32 s41, s46, s41
	s_add_i32 s46, s46, s41
	s_mul_hi_u32 s41, s15, s46
	s_mul_i32 s46, s41, s36
	s_sub_i32 s15, s15, s46
	s_add_i32 s47, s41, 1
	s_sub_i32 s46, s15, s36
	s_cmp_ge_u32 s15, s36
	s_cselect_b32 s41, s47, s41
	s_cselect_b32 s15, s46, s15
	s_add_i32 s46, s41, 1
	s_cmp_ge_u32 s15, s36
	s_cselect_b32 s15, s46, s41
	s_xor_b32 s15, s15, s37
	s_sub_i32 s36, s15, s37
	s_mul_i32 s15, s36, s35
	s_sub_i32 s6, s6, s15
	s_add_i32 s46, s34, s6
;     __device__ __forceinline__ const char* pa(const Gemm& g, const Unit& u, size_t tstep) const { return (const char*)g.A + (size_t)u.pm * tstep; }
;     __device__ __forceinline__ const char* pb(const Gemm& g, const Unit& u, size_t tstep) const { return (const char*)g.Bt + (size_t)u.pn * tstep; }
;     __device__ __forceinline__ const char* pa(const Gemm& g, const Unit& u, size_t tstep) const { return (const char*)g.A + (size_t)(u.pn >> 1) * 512 + (size_t)u.pm * tstep; }
;     __device__ __forceinline__ const char* pa(const Gemm& g, const Unit& u, size_t tstep) const { return (const char*)g.A + (size_t)u.seg * astride + (size_t)u.pm * tstep; }
;     __device__ __forceinline__ const char* pb(const Gemm& g, const Unit& u, size_t tstep) const { return (const char*)g.Bt + (size_t)u.seg * bstride + (size_t)u.pn * tstep; }
; #define PG8_STAGE(bufoff, gbase, voff) do { _Pragma("unroll") for (int _i = 0; _i < 2; ++_i) \
;         __builtin_amdgcn_global_load_lds((const unsigned*)((const char*)(gbase) + (voff)[_i]), (PG8_LAS unsigned*)(lds + (bufoff) + ldsw + _i * 8192), 16, 0, 0); } while (0)
; #define PG8_WAIT_V(n) asm volatile("s_waitcnt vmcnt(" #n ")" ::: "memory")
; #define PG8_WAIT_L(n) asm volatile("s_waitcnt lgkmcnt(" #n ")" ::: "memory")
; #define PG8_BAR __builtin_amdgcn_s_barrier()
;     ...
;         const char* nA = has_next ? S.pa(g, nxt, tstepA) : cA; const char* nB = has_next ? S.pb(g, nxt, tstepB) : cB;
;         for (int t = 0; t < nt; t += 2) {
;             const bool last = (t == nt - 2);
;             const char* a1 = cA + (size_t)(t + 1) * kstep;
;             const char* a2 = last ? nA : cA + (size_t)(t + 2) * kstep; const char* b2 = last ? nB : cB + (size_t)(t + 2) * kstep;
;             const char* a3 = a2 + kstep; const char* b3 = b2 + kstep;
;             if (last && has_next) S.a_ready(nxt);
;             if constexpr (SP2) {
;             PG8_LDB(B0, 0, 0); PG8_LDB(B1, 0, 1); PG8_SCHED; PG8_LDA(At, 0, 0); PG8_STAGE(PG8_SA(1, 1), a1 + hstepA, voffA);
;             PG8_WAIT_V(8); PG8_WAIT_L(0); PG8_BAR; PG8_MMA(0, 0, At, B0); PG8_MMA(0, 1, At, B1); PG8_BAR; PG8_SCHED;
;             PG8_LDA(At, 0, 1); PG8_STAGE(PG8_SB(0, 0), b2, voffB); PG8_STAGE(PG8_SB(0, 1), b2 + hstepB, voffB); PG8_STAGE(PG8_SA(0, 0), a2, voffA);
;             PG8_WAIT_V(8); PG8_WAIT_L(0); PG8_BAR; PG8_MMA(1, 0, At, B0); PG8_MMA(1, 1, At, B1); PG8_BAR; PG8_SCHED;
.LBB0_922:
	s_ashr_i32 s47, s46, 31
	s_lshl_b64 s[34:35], s[46:47], 20
	s_add_u32 s48, s60, s34
	s_addc_u32 s49, s61, s35
	s_and_b64 s[34:35], s[38:39], exec
	s_cselect_b32 s6, s49, s53
	s_cselect_b32 s15, s48, s52
	s_ashr_i32 s37, s36, 31
	s_lshl_b64 s[34:35], s[36:37], 20
	s_add_u32 s50, s62, s34
	s_addc_u32 s51, s63, s35
	s_and_b64 s[34:35], s[38:39], exec
	s_cselect_b32 s34, s51, s57
	s_cselect_b32 s35, s50, s56
	s_add_u32 s52, s52, 0x80080
	s_addc_u32 s53, s53, 0
	s_add_u32 s37, s56, 0x100
	s_addc_u32 s41, s57, 0
	s_mov_b32 s47, -2
	s_add_u32 s56, s52, 0xfff80080
	s_addc_u32 s57, s53, -1
	s_add_i32 s68, 0, 0x10000
	s_cmp_eq_u32 s47, 28
	s_cselect_b32 s59, s6, s57
	s_cselect_b32 s58, s15, s56
	s_cselect_b32 s57, s34, s41
	s_cselect_b32 s56, s35, s37
	s_add_i32 s76, 0, 0x14000
	s_waitcnt vmcnt(0)
	s_add_i32 m0, s10, 0xc000
	global_load_lds_dwordx4 v148, s[52:53]
	s_add_i32 m0, s10, 0xe000
	s_nop 0
	global_load_lds_dwordx4 v150, s[52:53]
	s_waitcnt vmcnt(8)
	s_waitcnt lgkmcnt(0)
	s_barrier
	v_mfma_f32_16x16x32_bf16 v[128:131], v[132:135], v[202:205], 0
	v_mfma_f32_16x16x32_bf16 v[124:127], v[156:159], v[202:205], 0
	v_mfma_f32_16x16x32_bf16 v[112:115], v[132:135], v[210:213], 0
	v_mfma_f32_16x16x32_bf16 v[108:111], v[156:159], v[210:213], 0
	v_mfma_f32_16x16x32_bf16 v[96:99], v[132:135], v[218:221], 0
	v_mfma_f32_16x16x32_bf16 v[92:95], v[156:159], v[218:221], 0
	v_mfma_f32_16x16x32_bf16 v[80:83], v[132:135], v[234:237], 0
	v_mfma_f32_16x16x32_bf16 v[76:79], v[156:159], v[234:237], 0
	v_mfma_f32_16x16x32_bf16 v[128:131], v[136:139], v[206:209], v[128:131]
	v_mfma_f32_16x16x32_bf16 v[124:127], v[160:163], v[206:209], v[124:127]
	v_mfma_f32_16x16x32_bf16 v[112:115], v[136:139], v[214:217], v[112:115]
	v_mfma_f32_16x16x32_bf16 v[108:111], v[160:163], v[214:217], v[108:111]
	v_mfma_f32_16x16x32_bf16 v[96:99], v[136:139], v[222:225], v[96:99]
	v_mfma_f32_16x16x32_bf16 v[92:95], v[160:163], v[222:225], v[92:95]
	v_mfma_f32_16x16x32_bf16 v[80:83], v[136:139], v[238:241], v[80:83]
	v_mfma_f32_16x16x32_bf16 v[76:79], v[160:163], v[238:241], v[76:79]
	v_mfma_f32_16x16x32_bf16 v[120:123], v[186:189], v[202:205], 0
	v_mfma_f32_16x16x32_bf16 v[116:119], v[194:197], v[202:205], 0
	v_mfma_f32_16x16x32_bf16 v[104:107], v[186:189], v[210:213], 0
	v_mfma_f32_16x16x32_bf16 v[100:103], v[194:197], v[210:213], 0
	v_mfma_f32_16x16x32_bf16 v[88:91], v[186:189], v[218:221], 0
	v_mfma_f32_16x16x32_bf16 v[84:87], v[194:197], v[218:221], 0
	v_mfma_f32_16x16x32_bf16 v[72:75], v[186:189], v[234:237], 0
	v_mfma_f32_16x16x32_bf16 v[68:71], v[194:197], v[234:237], 0
	v_mfma_f32_16x16x32_bf16 v[120:123], v[190:193], v[206:209], v[120:123]
	v_mfma_f32_16x16x32_bf16 v[116:119], v[198:201], v[206:209], v[116:119]
	v_mfma_f32_16x16x32_bf16 v[104:107], v[190:193], v[214:217], v[104:107]
	v_mfma_f32_16x16x32_bf16 v[100:103], v[198:201], v[214:217], v[100:103]
	v_mfma_f32_16x16x32_bf16 v[88:91], v[190:193], v[222:225], v[88:91]
	v_mfma_f32_16x16x32_bf16 v[84:87], v[198:201], v[222:225], v[84:87]
	v_mfma_f32_16x16x32_bf16 v[72:75], v[190:193], v[238:241], v[72:75]
	v_mfma_f32_16x16x32_bf16 v[68:71], v[198:201], v[238:241], v[68:71]
	s_barrier
	s_add_i32 s68, s68, s9
	s_mov_b32 m0, s68
	ds_read_b128 v[202:205], v155 offset:16384
	ds_read_b128 v[206:209], v155 offset:17408
	ds_read_b128 v[210:213], v155 offset:18432
	ds_read_b128 v[214:217], v155 offset:19456
	ds_read_b128 v[218:221], v155 offset:20480
	ds_read_b128 v[222:225], v155 offset:21504
	ds_read_b128 v[234:237], v155 offset:22528
	ds_read_b128 v[238:241], v155 offset:23552
	global_load_lds_dwordx4 v142, s[56:57]
	s_add_i32 m0, s68, 0x2000
	s_add_u32 s70, s56, 0x80000
	s_addc_u32 s71, s57, 0
	s_add_i32 s68, s76, s9
	global_load_lds_dwordx4 v146, s[56:57]
	s_mov_b32 m0, s68
	s_add_u32 s98, s58, 0x80
	s_addc_u32 s99, s59, 0
	global_load_lds_dwordx4 v142, s[70:71]
	s_add_i32 m0, s68, 0x2000
	s_nop 0
	global_load_lds_dwordx4 v146, s[70:71]
	s_mov_b32 m0, s10
	s_nop 0
	global_load_lds_dwordx4 v140, s[58:59]
	s_mov_b32 m0, s11
	s_nop 0
	global_load_lds_dwordx4 v144, s[58:59]
	s_waitcnt vmcnt(8)
	s_waitcnt lgkmcnt(0)
	s_barrier
	v_mfma_f32_16x16x32_bf16 v[64:67], v[132:135], v[202:205], 0
	v_mfma_f32_16x16x32_bf16 v[60:63], v[156:159], v[202:205], 0
	v_mfma_f32_16x16x32_bf16 v[48:51], v[132:135], v[210:213], 0
	v_mfma_f32_16x16x32_bf16 v[44:47], v[156:159], v[210:213], 0
	v_mfma_f32_16x16x32_bf16 v[30:33], v[132:135], v[218:221], 0
	v_mfma_f32_16x16x32_bf16 v[26:29], v[156:159], v[218:221], 0
	v_mfma_f32_16x16x32_bf16 v[14:17], v[132:135], v[234:237], 0
	v_mfma_f32_16x16x32_bf16 v[10:13], v[156:159], v[234:237], 0
	v_mfma_f32_16x16x32_bf16 v[64:67], v[136:139], v[206:209], v[64:67]
	v_mfma_f32_16x16x32_bf16 v[60:63], v[160:163], v[206:209], v[60:63]
	v_mfma_f32_16x16x32_bf16 v[48:51], v[136:139], v[214:217], v[48:51]
	v_mfma_f32_16x16x32_bf16 v[44:47], v[160:163], v[214:217], v[44:47]
	v_mfma_f32_16x16x32_bf16 v[30:33], v[136:139], v[222:225], v[30:33]
	v_mfma_f32_16x16x32_bf16 v[26:29], v[160:163], v[222:225], v[26:29]
	v_mfma_f32_16x16x32_bf16 v[14:17], v[136:139], v[238:241], v[14:17]
	v_mfma_f32_16x16x32_bf16 v[10:13], v[160:163], v[238:241], v[10:13]
	v_mfma_f32_16x16x32_bf16 v[56:59], v[186:189], v[202:205], 0
	v_mfma_f32_16x16x32_bf16 v[52:55], v[194:197], v[202:205], 0
	v_mfma_f32_16x16x32_bf16 v[40:43], v[186:189], v[210:213], 0
	v_mfma_f32_16x16x32_bf16 v[36:39], v[194:197], v[210:213], 0
	v_mfma_f32_16x16x32_bf16 v[22:25], v[186:189], v[218:221], 0
	v_mfma_f32_16x16x32_bf16 v[18:21], v[194:197], v[218:221], 0
	v_mfma_f32_16x16x32_bf16 v[6:9], v[186:189], v[234:237], 0
	v_mfma_f32_16x16x32_bf16 v[2:5], v[194:197], v[234:237], 0
	v_mfma_f32_16x16x32_bf16 v[56:59], v[190:193], v[206:209], v[56:59]
	v_mfma_f32_16x16x32_bf16 v[52:55], v[198:201], v[206:209], v[52:55]
	v_mfma_f32_16x16x32_bf16 v[40:43], v[190:193], v[214:217], v[40:43]
	v_mfma_f32_16x16x32_bf16 v[36:39], v[198:201], v[214:217], v[36:39]
	v_mfma_f32_16x16x32_bf16 v[22:25], v[190:193], v[222:225], v[22:25]
	v_mfma_f32_16x16x32_bf16 v[18:21], v[198:201], v[222:225], v[18:21]
	v_mfma_f32_16x16x32_bf16 v[6:9], v[190:193], v[238:241], v[6:9]
	v_mfma_f32_16x16x32_bf16 v[2:5], v[198:201], v[238:241], v[2:5]
	s_barrier
	s_branch .Lpeel_mid_923
	.p2align	6

;     __device__ __forceinline__ const char* pa(const Gemm& g, const Unit& u, size_t tstep) const { return (const char*)g.A + (size_t)u.pm * tstep; }
;     __device__ __forceinline__ const char* pb(const Gemm& g, const Unit& u, size_t tstep) const { return (const char*)g.Bt + (size_t)u.pn * tstep; }
;     __device__ __forceinline__ const char* pa(const Gemm& g, const Unit& u, size_t tstep) const { return (const char*)g.A + (size_t)(u.pn >> 1) * 512 + (size_t)u.pm * tstep; }
;     __device__ __forceinline__ bool next(int i, Unit& u) const { const int ti = i / 3, sg = i - 3 * ti; if (!StaticOrder::next(ti, u)) return false; u.seg = sg; return true; }
; #define PG8_WAIT_V(n) asm volatile("s_waitcnt vmcnt(" #n ")" ::: "memory")
;     __host__ __device__ __forceinline__ bool next(int i, Unit& u) const {
;         const long L = (long)i * G + c; if (L >= nwg) return false;
;         int wgid = (int)L; { const int q = nwg / NXCD, r = nwg % NXCD, xcd = wgid % NXCD, off = wgid / NXCD; wgid = (xcd < r ? xcd * (q + 1) : r * (q + 1) + (xcd - r) * q) + off; }
;         const int nig = WGM * nN, gid = wgid / nig, fm = gid * WGM, gsz = (nM - fm) < WGM ? (nM - fm) : WGM;
;         u.pm = fm + ((wgid % nig) % gsz); u.pn = (wgid % nig) / gsz; u.seg = 0; return true;
;     }
;     ...
;         const char* nA = has_next ? S.pa(g, nxt, tstepA) : cA; const char* nB = has_next ? S.pb(g, nxt, tstepB) : cB;
;         for (int t = 0; t < nt; t += 2) {
;             const bool last = (t == nt - 2);
;             const char* a1 = cA + (size_t)(t + 1) * kstep;
;             const char* a2 = last ? nA : cA + (size_t)(t + 2) * kstep; const char* b2 = last ? nB : cB + (size_t)(t + 2) * kstep;
;             const char* a3 = a2 + kstep; const char* b3 = b2 + kstep;
;             if (last && has_next) S.a_ready(nxt);
;             if constexpr (SP2) {
;             PG8_LDB(B0, 0, 0); PG8_LDB(B1, 0, 1); PG8_SCHED; PG8_LDA(At, 0, 0); PG8_STAGE(PG8_SA(1, 1), a1 + hstepA, voffA);
;             PG8_WAIT_V(8); PG8_WAIT_L(0); PG8_BAR; PG8_MMA(0, 0, At, B0); PG8_MMA(0, 1, At, B1); PG8_BAR; PG8_SCHED;
;             PG8_LDA(At, 0, 1); PG8_STAGE(PG8_SB(0, 0), b2, voffB); PG8_STAGE(PG8_SB(0, 1), b2 + hstepB, voffB); PG8_STAGE(PG8_SA(0, 0), a2, voffA);
;             PG8_WAIT_V(8); PG8_WAIT_L(0); PG8_BAR; PG8_MMA(1, 0, At, B0); PG8_MMA(1, 1, At, B1); PG8_BAR; PG8_SCHED;
.LBB0_1130:
	v_add_u32_e32 v226, 0x10000, v208
	ds_read_b128 v[26:29], v226
	ds_read_b128 v[30:33], v226 offset:1024
	ds_read_b128 v[18:21], v226 offset:2048
	ds_read_b128 v[22:25], v226 offset:3072
	ds_read_b128 v[10:13], v226 offset:16384
	ds_read_b128 v[14:17], v226 offset:17408
	ds_read_b128 v[2:5], v226 offset:18432
	ds_read_b128 v[6:9], v226 offset:19456
	ds_read_b128 v[198:201], v209
	ds_read_b128 v[202:205], v209 offset:1024
	ds_read_b128 v[210:213], v209 offset:2048
	ds_read_b128 v[214:217], v209 offset:3072
	ds_read_b128 v[218:221], v209 offset:4096
	ds_read_b128 v[222:225], v209 offset:5120
	ds_read_b128 v[234:237], v209 offset:6144
	ds_read_b128 v[238:241], v209 offset:7168
	s_add_i32 s66, s66, 1
	s_mul_i32 s31, s66, s59
	s_mul_hi_u32 s37, s66, s10
	s_add_i32 s37, s37, s31
	s_mul_i32 s31, s66, s10
	s_add_u32 s40, s31, s9
	s_addc_u32 s41, s37, s56
	v_cmp_gt_i64_e32 vcc, s[40:41], v[180:181]
	v_cmp_lt_i64_e64 s[38:39], s[40:41], v[178:179]
	s_cbranch_vccnz .LBB0_1132
	s_ashr_i32 s30, s40, 31
	s_lshr_b32 s30, s30, 29
	s_add_i32 s30, s40, s30
	s_ashr_i32 s31, s30, 3
	s_and_b32 s30, s30, -8
	s_sub_i32 s30, s40, s30
	s_cmp_lt_i32 s30, 0
	s_movk_i32 s36, 0xc1
	s_cselect_b32 s36, s36, 0xc0
	s_mul_i32 s30, s30, s36
	s_add_i32 s30, s30, s31
	s_mul_hi_i32 s31, s30, 0x2aaaaaab
	s_lshr_b32 s36, s31, 31
	s_ashr_i32 s31, s31, 5
	s_add_i32 s31, s31, s36
	s_lshl_b32 s36, s31, 3
	s_sub_i32 s37, 64, s36
	s_min_i32 s37, s37, 8
	s_abs_i32 s40, s37
	v_cvt_f32_u32_e32 v249, s40
	s_sub_i32 s46, 0, s40
	s_mulk_i32 s31, 0xc0
	s_sub_i32 s31, s30, s31
	v_rcp_iflag_f32_e32 v249, v249
	s_abs_i32 s30, s31
	s_xor_b32 s41, s31, s37
	s_ashr_i32 s41, s41, 31
	v_mul_f32_e32 v249, 0x4f7ffffe, v249
	v_cvt_u32_f32_e32 v249, v249
	s_nop 0
	v_readfirstlane_b32 s47, v249
	s_mul_i32 s46, s46, s47
	s_mul_hi_u32 s46, s47, s46
	s_add_i32 s47, s47, s46
	s_mul_hi_u32 s46, s30, s47
	s_mul_i32 s47, s46, s40
	s_sub_i32 s30, s30, s47
	s_add_i32 s54, s46, 1
	s_sub_i32 s47, s30, s40
	s_cmp_ge_u32 s30, s40
	s_cselect_b32 s46, s54, s46
	s_cselect_b32 s30, s47, s30
	s_add_i32 s47, s46, 1
	s_cmp_ge_u32 s30, s40
	s_cselect_b32 s30, s47, s46
	s_xor_b32 s30, s30, s41
	s_sub_i32 s30, s30, s41
	s_mul_i32 s37, s30, s37
	s_sub_i32 s31, s31, s37
	s_add_i32 s36, s36, s31
.LBB0_1132:
	s_ashr_i32 s37, s36, 31
	s_lshl_b64 s[40:41], s[36:37], 19
	s_add_u32 s40, s12, s40
	s_addc_u32 s41, s13, s41
	s_and_b64 s[46:47], s[38:39], exec
	s_cselect_b32 s37, s41, s51
	s_cselect_b32 s67, s40, s50
	s_ashr_i32 s31, s30, 31
	s_lshl_b64 s[46:47], s[30:31], 19
	s_add_u32 s46, s7, s46
	s_addc_u32 s47, s8, s47
	s_and_b64 s[54:55], s[38:39], exec
	s_cselect_b32 s31, s47, s53
	s_cselect_b32 s68, s46, s52
	s_add_u32 s50, s50, 0x40080
	s_addc_u32 s51, s51, 0
	s_add_u32 s70, s52, 0x100
	s_addc_u32 s71, s53, 0
	s_mov_b32 s74, -2
	s_add_u32 s52, s50, 0xfffc0080
	s_addc_u32 s53, s51, -1
	s_add_i32 s75, 0, 0x10000
	s_cmp_eq_u32 s74, 12
	s_cselect_b32 s55, s37, s53
	s_cselect_b32 s54, s67, s52
	s_cselect_b32 s53, s31, s71
	s_cselect_b32 s52, s68, s70
	s_add_i32 s76, 0, 0x14000
	s_add_i32 m0, s57, 0xc000
	global_load_lds_dwordx4 v194, s[50:51]
	s_add_i32 m0, s57, 0xe000
	s_nop 0
	global_load_lds_dwordx4 v196, s[50:51]
	s_waitcnt vmcnt(8)
	s_waitcnt lgkmcnt(0)
	s_barrier
	v_mfma_f32_16x16x128_f8f6f4 v[160:163], v[26:33], v[198:205], 0
	v_mfma_f32_16x16x128_f8f6f4 v[156:159], v[18:25], v[198:205], 0
	v_mfma_f32_16x16x128_f8f6f4 v[144:147], v[26:33], v[210:217], 0
	v_mfma_f32_16x16x128_f8f6f4 v[140:143], v[18:25], v[210:217], 0
	v_mfma_f32_16x16x128_f8f6f4 v[128:131], v[26:33], v[218:225], 0
	v_mfma_f32_16x16x128_f8f6f4 v[124:127], v[18:25], v[218:225], 0
	v_mfma_f32_16x16x128_f8f6f4 v[112:115], v[26:33], v[234:241], 0
	v_mfma_f32_16x16x128_f8f6f4 v[108:111], v[18:25], v[234:241], 0
	v_mfma_f32_16x16x128_f8f6f4 v[152:155], v[10:17], v[198:205], 0
	v_mfma_f32_16x16x128_f8f6f4 v[148:151], v[2:9], v[198:205], 0
	v_mfma_f32_16x16x128_f8f6f4 v[136:139], v[10:17], v[210:217], 0
	v_mfma_f32_16x16x128_f8f6f4 v[132:135], v[2:9], v[210:217], 0
	v_mfma_f32_16x16x128_f8f6f4 v[120:123], v[10:17], v[218:225], 0
	v_mfma_f32_16x16x128_f8f6f4 v[116:119], v[2:9], v[218:225], 0
	v_mfma_f32_16x16x128_f8f6f4 v[104:107], v[10:17], v[234:241], 0
	v_mfma_f32_16x16x128_f8f6f4 v[100:103], v[2:9], v[234:241], 0
	s_barrier
	s_add_i32 s75, s75, s11
	s_mov_b32 m0, s75
	ds_read_b128 v[210:213], v209 offset:16384
	ds_read_b128 v[214:217], v209 offset:17408
	ds_read_b128 v[218:221], v209 offset:18432
	ds_read_b128 v[222:225], v209 offset:19456
	ds_read_b128 v[234:237], v209 offset:20480
	ds_read_b128 v[238:241], v209 offset:21504
	ds_read_b128 v[242:245], v209 offset:22528
	ds_read_b128 v[246:249], v209 offset:23552
	global_load_lds_dwordx4 v34, s[52:53]
	s_add_i32 m0, s75, 0x2000
	s_add_u32 s78, s52, 0x40000
	s_addc_u32 s79, s53, 0
	s_add_i32 s75, s76, s11
	global_load_lds_dwordx4 v186, s[52:53]
	s_mov_b32 m0, s75
	s_add_u32 s98, s54, 0x80
	s_addc_u32 s99, s55, 0
	global_load_lds_dwordx4 v34, s[78:79]
	s_add_i32 m0, s75, 0x2000
	s_nop 0
	global_load_lds_dwordx4 v186, s[78:79]
	s_mov_b32 m0, s57
	s_nop 0
	global_load_lds_dwordx4 v190, s[54:55]
	s_mov_b32 m0, s6
	s_nop 0
	global_load_lds_dwordx4 v188, s[54:55]
	s_waitcnt vmcnt(8)
	s_waitcnt lgkmcnt(0)
	s_barrier
	v_mfma_f32_16x16x128_f8f6f4 v[96:99], v[26:33], v[210:217], 0
	v_mfma_f32_16x16x128_f8f6f4 v[92:95], v[18:25], v[210:217], 0
	v_mfma_f32_16x16x128_f8f6f4 v[80:83], v[26:33], v[218:225], 0
	v_mfma_f32_16x16x128_f8f6f4 v[76:79], v[18:25], v[218:225], 0
	v_mfma_f32_16x16x128_f8f6f4 v[64:67], v[26:33], v[234:241], 0
	v_mfma_f32_16x16x128_f8f6f4 v[60:63], v[18:25], v[234:241], 0
	v_mfma_f32_16x16x128_f8f6f4 v[48:51], v[26:33], v[242:249], 0
	v_mfma_f32_16x16x128_f8f6f4 v[44:47], v[18:25], v[242:249], 0
	v_mfma_f32_16x16x128_f8f6f4 v[88:91], v[10:17], v[210:217], 0
	v_mfma_f32_16x16x128_f8f6f4 v[84:87], v[2:9], v[210:217], 0
	v_mfma_f32_16x16x128_f8f6f4 v[72:75], v[10:17], v[218:225], 0
	v_mfma_f32_16x16x128_f8f6f4 v[68:71], v[2:9], v[218:225], 0
	v_mfma_f32_16x16x128_f8f6f4 v[56:59], v[10:17], v[234:241], 0
	v_mfma_f32_16x16x128_f8f6f4 v[52:55], v[2:9], v[234:241], 0
	v_mfma_f32_16x16x128_f8f6f4 v[40:43], v[10:17], v[242:249], 0
	v_mfma_f32_16x16x128_f8f6f4 v[36:39], v[2:9], v[242:249], 0
	s_barrier
	s_branch .Lpeel_mid_1133
	.p2align	6

;     __device__ __forceinline__ bool next(int i, Unit& u) const { const int ti = i / 3, sg = i - 3 * ti; if (!StaticOrder::next(ti, u)) return false; u.seg = sg; return true; }
;     __host__ __device__ __forceinline__ bool next(int i, Unit& u) const {
;         const long L = (long)i * G + c; if (L >= nwg) return false;
;         int wgid = (int)L; { const int q = nwg / NXCD, r = nwg % NXCD, xcd = wgid % NXCD, off = wgid / NXCD; wgid = (xcd < r ? xcd * (q + 1) : r * (q + 1) + (xcd - r) * q) + off; }
;         const int nig = WGM * nN, gid = wgid / nig, fm = gid * WGM, gsz = (nM - fm) < WGM ? (nM - fm) : WGM;
;         u.pm = fm + ((wgid % nig) % gsz); u.pn = (wgid % nig) / gsz; u.seg = 0; return true;
;     }
.LBB0_1150:
	v_add_u32_e32 v162, 0x10000, v155
	ds_read_b128 v[132:135], v162
	ds_read_b128 v[136:139], v162 offset:1024
	ds_read_b128 v[158:161], v162 offset:2048
	ds_read_b128 v[186:189], v162 offset:3072
	ds_read_b128 v[190:193], v162 offset:16384
	ds_read_b128 v[194:197], v162 offset:17408
	ds_read_b128 v[198:201], v162 offset:18432
	ds_read_b128 v[202:205], v162 offset:19456
	ds_read_b128 v[206:209], v157
	ds_read_b128 v[210:213], v157 offset:1024
	ds_read_b128 v[214:217], v157 offset:2048
	ds_read_b128 v[218:221], v157 offset:3072
	ds_read_b128 v[222:225], v157 offset:4096
	ds_read_b128 v[234:237], v157 offset:5120
	ds_read_b128 v[238:241], v157 offset:6144
	ds_read_b128 v[242:245], v157 offset:7168
	s_add_i32 s76, s76, 1
	s_mul_i32 s6, s76, s74
	s_mul_hi_u32 s10, s76, s64
	s_add_i32 s10, s10, s6
	s_mul_i32 s6, s76, s64
	s_add_u32 s50, s6, s65
	s_addc_u32 s51, s10, s75
	v_cmp_gt_i64_e32 vcc, s[50:51], v[184:185]
	v_cmp_lt_i64_e64 s[38:39], s[50:51], v[182:183]
	s_cbranch_vccnz .LBB0_1152
	s_ashr_i32 s6, s50, 31
	s_lshr_b32 s6, s6, 29
	s_add_i32 s6, s50, s6
	s_ashr_i32 s10, s6, 3
	s_and_b32 s6, s6, -8
	s_sub_i32 s6, s50, s6
	s_cmp_lt_i32 s6, 0
	s_movk_i32 s11, 0x1e1
	s_cselect_b32 s11, s11, 0x1e0
	s_mul_i32 s6, s6, s11
	s_add_i32 s6, s6, s10
	s_mul_hi_i32 s10, s6, 0x88888889
	s_add_i32 s10, s10, s6
	s_lshr_b32 s11, s10, 31
	s_ashr_i32 s10, s10, 8
	s_add_i32 s10, s10, s11
	s_lshl_b32 s11, s10, 3
	s_sub_i32 s12, 64, s11
	s_min_i32 s12, s12, 8
	s_abs_i32 s13, s12
	v_cvt_f32_u32_e32 v2, s13
	s_sub_i32 s18, 0, s13
	s_mulk_i32 s10, 0x1e0
	s_sub_i32 s6, s6, s10
	v_rcp_iflag_f32_e32 v2, v2
	s_abs_i32 s10, s6
	s_xor_b32 s15, s6, s12
	s_ashr_i32 s15, s15, 31
	v_mul_f32_e32 v2, 0x4f7ffffe, v2
	v_cvt_u32_f32_e32 v2, v2
	s_nop 0
	v_readfirstlane_b32 s19, v2
	s_mul_i32 s18, s18, s19
	s_mul_hi_u32 s18, s19, s18
	s_add_i32 s19, s19, s18
	s_mul_hi_u32 s18, s10, s19
	s_mul_i32 s19, s18, s13
	s_sub_i32 s10, s10, s19
	s_add_i32 s34, s18, 1
	s_sub_i32 s19, s10, s13
	s_cmp_ge_u32 s10, s13
	s_cselect_b32 s18, s34, s18
	s_cselect_b32 s10, s19, s10
	s_add_i32 s19, s18, 1
	s_cmp_ge_u32 s10, s13
	s_cselect_b32 s10, s19, s18
	s_xor_b32 s10, s10, s15
	s_sub_i32 s18, s10, s15
	s_mul_i32 s10, s18, s12
	s_sub_i32 s6, s6, s10
	s_add_i32 s48, s11, s6
;     __device__ __forceinline__ const char* pa(const Gemm& g, const Unit& u, size_t tstep) const { return (const char*)g.A + (size_t)u.pm * tstep; }
;     __device__ __forceinline__ const char* pb(const Gemm& g, const Unit& u, size_t tstep) const { return (const char*)g.Bt + (size_t)u.pn * tstep; }
;     __device__ __forceinline__ const char* pa(const Gemm& g, const Unit& u, size_t tstep) const { return (const char*)g.A + (size_t)(u.pn >> 1) * 512 + (size_t)u.pm * tstep; }
;     __device__ __forceinline__ const char* pa(const Gemm& g, const Unit& u, size_t tstep) const { return (const char*)g.A + (size_t)u.seg * astride + (size_t)u.pm * tstep; }
;     __device__ __forceinline__ const char* pb(const Gemm& g, const Unit& u, size_t tstep) const { return (const char*)g.Bt + (size_t)u.seg * bstride + (size_t)u.pn * tstep; }
; #define PG8_STAGE(bufoff, gbase, voff) do { _Pragma("unroll") for (int _i = 0; _i < 2; ++_i) \
;         __builtin_amdgcn_global_load_lds((const unsigned*)((const char*)(gbase) + (voff)[_i]), (PG8_LAS unsigned*)(lds + (bufoff) + ldsw + _i * 8192), 16, 0, 0); } while (0)
; #define PG8_WAIT_V(n) asm volatile("s_waitcnt vmcnt(" #n ")" ::: "memory")
; #define PG8_WAIT_L(n) asm volatile("s_waitcnt lgkmcnt(" #n ")" ::: "memory")
; #define PG8_BAR __builtin_amdgcn_s_barrier()
;     ...
;         const char* nA = has_next ? S.pa(g, nxt, tstepA) : cA; const char* nB = has_next ? S.pb(g, nxt, tstepB) : cB;
;         for (int t = 0; t < nt; t += 2) {
;             const bool last = (t == nt - 2);
;             const char* a1 = cA + (size_t)(t + 1) * kstep;
;             const char* a2 = last ? nA : cA + (size_t)(t + 2) * kstep; const char* b2 = last ? nB : cB + (size_t)(t + 2) * kstep;
;             const char* a3 = a2 + kstep; const char* b3 = b2 + kstep;
;             if (last && has_next) S.a_ready(nxt);
;             if constexpr (SP2) {
;             PG8_LDB(B0, 0, 0); PG8_LDB(B1, 0, 1); PG8_SCHED; PG8_LDA(At, 0, 0); PG8_STAGE(PG8_SA(1, 1), a1 + hstepA, voffA);
;             PG8_WAIT_V(8); PG8_WAIT_L(0); PG8_BAR; PG8_MMA(0, 0, At, B0); PG8_MMA(0, 1, At, B1); PG8_BAR; PG8_SCHED;
;             PG8_LDA(At, 0, 1); PG8_STAGE(PG8_SB(0, 0), b2, voffB); PG8_STAGE(PG8_SB(0, 1), b2 + hstepB, voffB); PG8_STAGE(PG8_SA(0, 0), a2, voffA);
;             PG8_WAIT_V(8); PG8_WAIT_L(0); PG8_BAR; PG8_MMA(1, 0, At, B0); PG8_MMA(1, 1, At, B1); PG8_BAR; PG8_SCHED;
.LBB0_1152:
	s_ashr_i32 s49, s48, 31
	s_lshl_b64 s[10:11], s[48:49], 20
	s_add_u32 s50, s60, s10
	s_addc_u32 s51, s61, s11
	s_and_b64 s[10:11], s[38:39], exec
	s_cselect_b32 s6, s51, s27
	s_cselect_b32 s10, s50, s26
	s_ashr_i32 s19, s18, 31
	s_lshl_b64 s[12:13], s[18:19], 20
	s_add_u32 s52, s62, s12
	s_addc_u32 s53, s63, s13
	s_and_b64 s[12:13], s[38:39], exec
	s_cselect_b32 s11, s53, s41
	s_cselect_b32 s12, s52, s40
	s_add_u32 s26, s26, 0x80080
	s_addc_u32 s27, s27, 0
	s_add_u32 s13, s40, 0x100
	s_addc_u32 s15, s41, 0
	s_mov_b32 s19, -2
	s_add_u32 s34, s26, 0xfff80080
	s_addc_u32 s35, s27, -1
	s_add_i32 s37, 0, 0x10000
	s_cmp_eq_u32 s19, 28
	s_cselect_b32 s57, s6, s35
	s_cselect_b32 s56, s10, s34
	s_cselect_b32 s41, s11, s15
	s_cselect_b32 s40, s12, s13
	s_add_i32 s49, 0, 0x14000
	s_waitcnt vmcnt(0)
	s_add_i32 m0, s8, 0xc000
	global_load_lds_dwordx4 v150, s[26:27]
	s_add_i32 m0, s8, 0xe000
	s_nop 0
	global_load_lds_dwordx4 v152, s[26:27]
	s_waitcnt vmcnt(8)
	s_waitcnt lgkmcnt(0)
	s_barrier
	v_mfma_f32_16x16x32_bf16 v[128:131], v[132:135], v[206:209], 0
	v_mfma_f32_16x16x32_bf16 v[124:127], v[158:161], v[206:209], 0
	v_mfma_f32_16x16x32_bf16 v[112:115], v[132:135], v[214:217], 0
	v_mfma_f32_16x16x32_bf16 v[108:111], v[158:161], v[214:217], 0
	v_mfma_f32_16x16x32_bf16 v[96:99], v[132:135], v[222:225], 0
	v_mfma_f32_16x16x32_bf16 v[92:95], v[158:161], v[222:225], 0
	v_mfma_f32_16x16x32_bf16 v[80:83], v[132:135], v[238:241], 0
	v_mfma_f32_16x16x32_bf16 v[76:79], v[158:161], v[238:241], 0
	v_mfma_f32_16x16x32_bf16 v[128:131], v[136:139], v[210:213], v[128:131]
	v_mfma_f32_16x16x32_bf16 v[124:127], v[186:189], v[210:213], v[124:127]
	v_mfma_f32_16x16x32_bf16 v[112:115], v[136:139], v[218:221], v[112:115]
	v_mfma_f32_16x16x32_bf16 v[108:111], v[186:189], v[218:221], v[108:111]
	v_mfma_f32_16x16x32_bf16 v[96:99], v[136:139], v[234:237], v[96:99]
	v_mfma_f32_16x16x32_bf16 v[92:95], v[186:189], v[234:237], v[92:95]
	v_mfma_f32_16x16x32_bf16 v[80:83], v[136:139], v[242:245], v[80:83]
	v_mfma_f32_16x16x32_bf16 v[76:79], v[186:189], v[242:245], v[76:79]
	v_mfma_f32_16x16x32_bf16 v[120:123], v[190:193], v[206:209], 0
	v_mfma_f32_16x16x32_bf16 v[116:119], v[198:201], v[206:209], 0
	v_mfma_f32_16x16x32_bf16 v[104:107], v[190:193], v[214:217], 0
	v_mfma_f32_16x16x32_bf16 v[100:103], v[198:201], v[214:217], 0
	v_mfma_f32_16x16x32_bf16 v[88:91], v[190:193], v[222:225], 0
	v_mfma_f32_16x16x32_bf16 v[84:87], v[198:201], v[222:225], 0
	v_mfma_f32_16x16x32_bf16 v[72:75], v[190:193], v[238:241], 0
	v_mfma_f32_16x16x32_bf16 v[68:71], v[198:201], v[238:241], 0
	v_mfma_f32_16x16x32_bf16 v[120:123], v[194:197], v[210:213], v[120:123]
	v_mfma_f32_16x16x32_bf16 v[116:119], v[202:205], v[210:213], v[116:119]
	v_mfma_f32_16x16x32_bf16 v[104:107], v[194:197], v[218:221], v[104:107]
	v_mfma_f32_16x16x32_bf16 v[100:103], v[202:205], v[218:221], v[100:103]
	v_mfma_f32_16x16x32_bf16 v[88:91], v[194:197], v[234:237], v[88:91]
	v_mfma_f32_16x16x32_bf16 v[84:87], v[202:205], v[234:237], v[84:87]
	v_mfma_f32_16x16x32_bf16 v[72:75], v[194:197], v[242:245], v[72:75]
	v_mfma_f32_16x16x32_bf16 v[68:71], v[202:205], v[242:245], v[68:71]
	s_barrier
	s_add_i32 s34, s37, s7
	s_mov_b32 m0, s34
	ds_read_b128 v[206:209], v157 offset:16384
	ds_read_b128 v[210:213], v157 offset:17408
	ds_read_b128 v[214:217], v157 offset:18432
	ds_read_b128 v[218:221], v157 offset:19456
	ds_read_b128 v[222:225], v157 offset:20480
	ds_read_b128 v[234:237], v157 offset:21504
	ds_read_b128 v[238:241], v157 offset:22528
	ds_read_b128 v[242:245], v157 offset:23552
	global_load_lds_dwordx4 v142, s[40:41]
	s_add_i32 m0, s34, 0x2000
	s_add_u32 s34, s40, 0x80000
	s_addc_u32 s35, s41, 0
	s_add_i32 s37, s49, s7
	global_load_lds_dwordx4 v146, s[40:41]
	s_mov_b32 m0, s37
	s_nop 0
	global_load_lds_dwordx4 v142, s[34:35]
	s_add_i32 m0, s37, 0x2000
	s_nop 0
	global_load_lds_dwordx4 v146, s[34:35]
	s_mov_b32 m0, s8
	s_nop 0
	global_load_lds_dwordx4 v140, s[56:57]
	s_mov_b32 m0, s9
	s_nop 0
	global_load_lds_dwordx4 v144, s[56:57]
	s_waitcnt vmcnt(8)
	s_waitcnt lgkmcnt(0)
	s_barrier
	v_mfma_f32_16x16x32_bf16 v[64:67], v[132:135], v[206:209], 0
	v_mfma_f32_16x16x32_bf16 v[60:63], v[158:161], v[206:209], 0
	v_mfma_f32_16x16x32_bf16 v[48:51], v[132:135], v[214:217], 0
	v_mfma_f32_16x16x32_bf16 v[44:47], v[158:161], v[214:217], 0
	v_mfma_f32_16x16x32_bf16 v[30:33], v[132:135], v[222:225], 0
	v_mfma_f32_16x16x32_bf16 v[26:29], v[158:161], v[222:225], 0
	v_mfma_f32_16x16x32_bf16 v[14:17], v[132:135], v[238:241], 0
	v_mfma_f32_16x16x32_bf16 v[10:13], v[158:161], v[238:241], 0
	v_mfma_f32_16x16x32_bf16 v[64:67], v[136:139], v[210:213], v[64:67]
	v_mfma_f32_16x16x32_bf16 v[60:63], v[186:189], v[210:213], v[60:63]
	v_mfma_f32_16x16x32_bf16 v[48:51], v[136:139], v[218:221], v[48:51]
	v_mfma_f32_16x16x32_bf16 v[44:47], v[186:189], v[218:221], v[44:47]
	v_mfma_f32_16x16x32_bf16 v[30:33], v[136:139], v[234:237], v[30:33]
	v_mfma_f32_16x16x32_bf16 v[26:29], v[186:189], v[234:237], v[26:29]
	v_mfma_f32_16x16x32_bf16 v[14:17], v[136:139], v[242:245], v[14:17]
	v_mfma_f32_16x16x32_bf16 v[10:13], v[186:189], v[242:245], v[10:13]
	v_mfma_f32_16x16x32_bf16 v[56:59], v[190:193], v[206:209], 0
	v_mfma_f32_16x16x32_bf16 v[52:55], v[198:201], v[206:209], 0
	v_mfma_f32_16x16x32_bf16 v[40:43], v[190:193], v[214:217], 0
	v_mfma_f32_16x16x32_bf16 v[36:39], v[198:201], v[214:217], 0
	v_mfma_f32_16x16x32_bf16 v[22:25], v[190:193], v[222:225], 0
	v_mfma_f32_16x16x32_bf16 v[18:21], v[198:201], v[222:225], 0
	v_mfma_f32_16x16x32_bf16 v[6:9], v[190:193], v[238:241], 0
	v_mfma_f32_16x16x32_bf16 v[2:5], v[198:201], v[238:241], 0
	v_mfma_f32_16x16x32_bf16 v[56:59], v[194:197], v[210:213], v[56:59]
	v_mfma_f32_16x16x32_bf16 v[52:55], v[202:205], v[210:213], v[52:55]
	v_mfma_f32_16x16x32_bf16 v[40:43], v[194:197], v[218:221], v[40:43]
	v_mfma_f32_16x16x32_bf16 v[36:39], v[202:205], v[218:221], v[36:39]
	v_mfma_f32_16x16x32_bf16 v[22:25], v[194:197], v[234:237], v[22:25]
	v_mfma_f32_16x16x32_bf16 v[18:21], v[202:205], v[234:237], v[18:21]
	v_mfma_f32_16x16x32_bf16 v[6:9], v[194:197], v[242:245], v[6:9]
	v_mfma_f32_16x16x32_bf16 v[2:5], v[202:205], v[242:245], v[2:5]
	s_barrier
	s_branch .Lpeel_mid_1153
	.p2align	6

;     __device__ __forceinline__ bool next(int i, Unit& u) const { const int ti = i / 3, sg = i - 3 * ti; if (!StaticOrder::next(ti, u)) return false; u.seg = sg; return true; }
;     __host__ __device__ __forceinline__ bool next(int i, Unit& u) const {
;         const long L = (long)i * G + c; if (L >= nwg) return false;
;         int wgid = (int)L; { const int q = nwg / NXCD, r = nwg % NXCD, xcd = wgid % NXCD, off = wgid / NXCD; wgid = (xcd < r ? xcd * (q + 1) : r * (q + 1) + (xcd - r) * q) + off; }
;         const int nig = WGM * nN, gid = wgid / nig, fm = gid * WGM, gsz = (nM - fm) < WGM ? (nM - fm) : WGM;
.LBB0_2131:
	v_add_u32_e32 v163, 0x10000, v143
	ds_read_b128 v[146:149], v163
	ds_read_b128 v[150:153], v163 offset:1024
	ds_read_b128 v[154:157], v163 offset:2048
	ds_read_b128 v[158:161], v163 offset:3072
	ds_read_b128 v[186:189], v163 offset:16384
	ds_read_b128 v[190:193], v163 offset:17408
	ds_read_b128 v[194:197], v163 offset:18432
	ds_read_b128 v[198:201], v163 offset:19456
	ds_read_b128 v[202:205], v145
	ds_read_b128 v[206:209], v145 offset:1024
	ds_read_b128 v[210:213], v145 offset:2048
	ds_read_b128 v[214:217], v145 offset:3072
	ds_read_b128 v[218:221], v145 offset:4096
	ds_read_b128 v[222:225], v145 offset:5120
	ds_read_b128 v[234:237], v145 offset:6144
	ds_read_b128 v[238:241], v145 offset:7168
	s_add_i32 s55, s55, 1
	s_mul_i32 s37, s55, s54
	s_mul_hi_u32 s38, s55, s8
	s_add_i32 s38, s38, s37
	s_mul_i32 s37, s55, s8
	s_add_u32 s42, s37, s7
	s_addc_u32 s43, s38, s9
	v_cmp_gt_i64_e32 vcc, s[42:43], v[170:171]
	v_cmp_lt_i64_e64 s[38:39], s[42:43], v[168:169]
	s_cbranch_vccnz .LBB0_2137
	s_ashr_i32 s36, s42, 31
	s_lshr_b32 s36, s36, 29
	s_add_i32 s40, s42, s36
	s_and_b32 s36, s40, -8
	s_sub_i32 s41, s42, s36
	s_cmp_gt_i32 s41, -1
	s_mov_b64 s[36:37], -1
	s_cbranch_scc0 .LBB0_2134
	s_lshl_b32 s42, s41, 6
	s_mov_b64 s[36:37], 0

;     __device__ __forceinline__ const char* pa(const Gemm& g, const Unit& u, size_t tstep) const { return (const char*)g.A + (size_t)u.pm * tstep; }
;     __device__ __forceinline__ const char* pb(const Gemm& g, const Unit& u, size_t tstep) const { return (const char*)g.Bt + (size_t)u.pn * tstep; }
;     __device__ __forceinline__ const char* pa(const Gemm& g, const Unit& u, size_t tstep) const { return (const char*)g.A + (size_t)(u.pn >> 1) * 512 + (size_t)u.pm * tstep; }
;     __device__ __forceinline__ const char* pa(const Gemm& g, const Unit& u, size_t tstep) const { return (const char*)g.A + (size_t)u.seg * astride + (size_t)u.pm * tstep; }
;     __device__ __forceinline__ const char* pb(const Gemm& g, const Unit& u, size_t tstep) const { return (const char*)g.Bt + (size_t)u.seg * bstride + (size_t)u.pn * tstep; }
; #define PG8_STAGE(bufoff, gbase, voff) do { _Pragma("unroll") for (int _i = 0; _i < 2; ++_i) \
;         __builtin_amdgcn_global_load_lds((const unsigned*)((const char*)(gbase) + (voff)[_i]), (PG8_LAS unsigned*)(lds + (bufoff) + ldsw + _i * 8192), 16, 0, 0); } while (0)
; #define PG8_WAIT_V(n) asm volatile("s_waitcnt vmcnt(" #n ")" ::: "memory")
; #define PG8_WAIT_L(n) asm volatile("s_waitcnt lgkmcnt(" #n ")" ::: "memory")
; #define PG8_BAR __builtin_amdgcn_s_barrier()
;     ...
;         const char* nA = has_next ? S.pa(g, nxt, tstepA) : cA; const char* nB = has_next ? S.pb(g, nxt, tstepB) : cB;
;         for (int t = 0; t < nt; t += 2) {
;             const bool last = (t == nt - 2);
;             const char* a1 = cA + (size_t)(t + 1) * kstep;
;             const char* a2 = last ? nA : cA + (size_t)(t + 2) * kstep; const char* b2 = last ? nB : cB + (size_t)(t + 2) * kstep;
;             const char* a3 = a2 + kstep; const char* b3 = b2 + kstep;
;             if (last && has_next) S.a_ready(nxt);
;             if constexpr (SP2) {
;             PG8_LDB(B0, 0, 0); PG8_LDB(B1, 0, 1); PG8_SCHED; PG8_LDA(At, 0, 0); PG8_STAGE(PG8_SA(1, 1), a1 + hstepA, voffA);
;             PG8_WAIT_V(8); PG8_WAIT_L(0); PG8_BAR; PG8_MMA(0, 0, At, B0); PG8_MMA(0, 1, At, B1); PG8_BAR; PG8_SCHED;
;             PG8_LDA(At, 0, 1); PG8_STAGE(PG8_SB(0, 0), b2, voffB); PG8_STAGE(PG8_SB(0, 1), b2 + hstepB, voffB); PG8_STAGE(PG8_SA(0, 0), a2, voffA);
;             PG8_WAIT_V(8); PG8_WAIT_L(0); PG8_BAR; PG8_MMA(1, 0, At, B0); PG8_MMA(1, 1, At, B1); PG8_BAR; PG8_SCHED;
.LBB0_2137:
	s_ashr_i32 s41, s40, 31
	s_lshl_b64 s[42:43], s[40:41], 20
	s_add_u32 s42, s10, s42
	s_addc_u32 s43, s11, s43
	s_and_b64 s[44:45], s[38:39], exec
	s_cselect_b32 s41, s43, s47
	s_cselect_b32 s56, s42, s46
	s_ashr_i32 s37, s36, 31
	s_lshl_b64 s[44:45], s[36:37], 20
	s_add_u32 s44, s12, s44
	s_addc_u32 s45, s13, s45
	s_and_b64 s[50:51], s[38:39], exec
	s_cselect_b32 s37, s45, s49
	s_cselect_b32 s57, s44, s48
	s_add_u32 s46, s46, 0x80080
	s_addc_u32 s47, s47, 0
	s_add_u32 s58, s48, 0x100
	s_addc_u32 s59, s49, 0
	s_mov_b32 s60, -2
	s_add_u32 s48, s46, 0xfff80080
	s_addc_u32 s49, s47, -1
	s_add_i32 s61, 0, 0x10000
	s_cmp_eq_u32 s60, 28
	s_cselect_b32 s51, s41, s49
	s_cselect_b32 s50, s56, s48
	s_cselect_b32 s49, s37, s59
	s_cselect_b32 s48, s57, s58
	s_add_i32 s64, 0, 0x14000
	s_add_i32 m0, s21, 0xc000
	global_load_lds_dwordx4 v138, s[46:47]
	s_add_i32 m0, s21, 0xe000
	s_nop 0
	global_load_lds_dwordx4 v140, s[46:47]
	s_waitcnt vmcnt(8)
	s_waitcnt lgkmcnt(0)
	s_barrier
	v_mfma_f32_16x16x32_bf16 v[128:131], v[146:149], v[202:205], 0
	v_mfma_f32_16x16x32_bf16 v[124:127], v[154:157], v[202:205], 0
	v_mfma_f32_16x16x32_bf16 v[120:123], v[146:149], v[210:213], 0
	v_mfma_f32_16x16x32_bf16 v[116:119], v[154:157], v[210:213], 0
	v_mfma_f32_16x16x32_bf16 v[104:107], v[146:149], v[218:221], 0
	v_mfma_f32_16x16x32_bf16 v[100:103], v[154:157], v[218:221], 0
	v_mfma_f32_16x16x32_bf16 v[88:91], v[146:149], v[234:237], 0
	v_mfma_f32_16x16x32_bf16 v[84:87], v[154:157], v[234:237], 0
	v_mfma_f32_16x16x32_bf16 v[128:131], v[150:153], v[206:209], v[128:131]
	v_mfma_f32_16x16x32_bf16 v[124:127], v[158:161], v[206:209], v[124:127]
	v_mfma_f32_16x16x32_bf16 v[120:123], v[150:153], v[214:217], v[120:123]
	v_mfma_f32_16x16x32_bf16 v[116:119], v[158:161], v[214:217], v[116:119]
	v_mfma_f32_16x16x32_bf16 v[104:107], v[150:153], v[222:225], v[104:107]
	v_mfma_f32_16x16x32_bf16 v[100:103], v[158:161], v[222:225], v[100:103]
	v_mfma_f32_16x16x32_bf16 v[88:91], v[150:153], v[238:241], v[88:91]
	v_mfma_f32_16x16x32_bf16 v[84:87], v[158:161], v[238:241], v[84:87]
	v_mfma_f32_16x16x32_bf16 v[112:115], v[186:189], v[202:205], 0
	v_mfma_f32_16x16x32_bf16 v[108:111], v[194:197], v[202:205], 0
	v_mfma_f32_16x16x32_bf16 v[96:99], v[186:189], v[210:213], 0
	v_mfma_f32_16x16x32_bf16 v[92:95], v[194:197], v[210:213], 0
	v_mfma_f32_16x16x32_bf16 v[80:83], v[186:189], v[218:221], 0
	v_mfma_f32_16x16x32_bf16 v[76:79], v[194:197], v[218:221], 0
	v_mfma_f32_16x16x32_bf16 v[72:75], v[186:189], v[234:237], 0
	v_mfma_f32_16x16x32_bf16 v[68:71], v[194:197], v[234:237], 0
	v_mfma_f32_16x16x32_bf16 v[112:115], v[190:193], v[206:209], v[112:115]
	v_mfma_f32_16x16x32_bf16 v[108:111], v[198:201], v[206:209], v[108:111]
	v_mfma_f32_16x16x32_bf16 v[96:99], v[190:193], v[214:217], v[96:99]
	v_mfma_f32_16x16x32_bf16 v[92:95], v[198:201], v[214:217], v[92:95]
	v_mfma_f32_16x16x32_bf16 v[80:83], v[190:193], v[222:225], v[80:83]
	v_mfma_f32_16x16x32_bf16 v[76:79], v[198:201], v[222:225], v[76:79]
	v_mfma_f32_16x16x32_bf16 v[72:75], v[190:193], v[238:241], v[72:75]
	v_mfma_f32_16x16x32_bf16 v[68:71], v[198:201], v[238:241], v[68:71]
	s_barrier
	s_add_i32 s61, s61, s15
	s_mov_b32 m0, s61
	ds_read_b128 v[202:205], v145 offset:16384
	ds_read_b128 v[206:209], v145 offset:17408
	ds_read_b128 v[210:213], v145 offset:18432
	ds_read_b128 v[214:217], v145 offset:19456
	ds_read_b128 v[218:221], v145 offset:20480
	ds_read_b128 v[222:225], v145 offset:21504
	ds_read_b128 v[234:237], v145 offset:22528
	ds_read_b128 v[238:241], v145 offset:23552
	global_load_lds_dwordx4 v34, s[48:49]
	s_add_i32 m0, s61, 0x2000
	s_add_u32 s62, s48, 0x80000
	s_addc_u32 s63, s49, 0
	s_add_i32 s61, s64, s15
	global_load_lds_dwordx4 v136, s[48:49]
	s_mov_b32 m0, s61
	s_add_u32 s98, s50, 0x80
	s_addc_u32 s99, s51, 0
	global_load_lds_dwordx4 v34, s[62:63]
	s_add_i32 m0, s61, 0x2000
	s_nop 0
	global_load_lds_dwordx4 v136, s[62:63]
	s_mov_b32 m0, s21
	s_nop 0
	global_load_lds_dwordx4 v132, s[50:51]
	s_mov_b32 m0, s34
	s_nop 0
	global_load_lds_dwordx4 v134, s[50:51]
	s_waitcnt vmcnt(8)
	s_waitcnt lgkmcnt(0)
	s_barrier
	v_mfma_f32_16x16x32_bf16 v[64:67], v[146:149], v[202:205], 0
	v_mfma_f32_16x16x32_bf16 v[60:63], v[154:157], v[202:205], 0
	v_mfma_f32_16x16x32_bf16 v[56:59], v[146:149], v[210:213], 0
	v_mfma_f32_16x16x32_bf16 v[52:55], v[154:157], v[210:213], 0
	v_mfma_f32_16x16x32_bf16 v[40:43], v[146:149], v[218:221], 0
	v_mfma_f32_16x16x32_bf16 v[36:39], v[154:157], v[218:221], 0
	v_mfma_f32_16x16x32_bf16 v[22:25], v[146:149], v[234:237], 0
	v_mfma_f32_16x16x32_bf16 v[18:21], v[154:157], v[234:237], 0
	v_mfma_f32_16x16x32_bf16 v[64:67], v[150:153], v[206:209], v[64:67]
	v_mfma_f32_16x16x32_bf16 v[60:63], v[158:161], v[206:209], v[60:63]
	v_mfma_f32_16x16x32_bf16 v[56:59], v[150:153], v[214:217], v[56:59]
	v_mfma_f32_16x16x32_bf16 v[52:55], v[158:161], v[214:217], v[52:55]
	v_mfma_f32_16x16x32_bf16 v[40:43], v[150:153], v[222:225], v[40:43]
	v_mfma_f32_16x16x32_bf16 v[36:39], v[158:161], v[222:225], v[36:39]
	v_mfma_f32_16x16x32_bf16 v[22:25], v[150:153], v[238:241], v[22:25]
	v_mfma_f32_16x16x32_bf16 v[18:21], v[158:161], v[238:241], v[18:21]
	v_mfma_f32_16x16x32_bf16 v[48:51], v[186:189], v[202:205], 0
	v_mfma_f32_16x16x32_bf16 v[44:47], v[194:197], v[202:205], 0
	v_mfma_f32_16x16x32_bf16 v[30:33], v[186:189], v[210:213], 0
	v_mfma_f32_16x16x32_bf16 v[26:29], v[194:197], v[210:213], 0
	v_mfma_f32_16x16x32_bf16 v[14:17], v[186:189], v[218:221], 0
	v_mfma_f32_16x16x32_bf16 v[10:13], v[194:197], v[218:221], 0
	v_mfma_f32_16x16x32_bf16 v[6:9], v[186:189], v[234:237], 0
	v_mfma_f32_16x16x32_bf16 v[2:5], v[194:197], v[234:237], 0
	v_mfma_f32_16x16x32_bf16 v[48:51], v[190:193], v[206:209], v[48:51]
	v_mfma_f32_16x16x32_bf16 v[44:47], v[198:201], v[206:209], v[44:47]
	v_mfma_f32_16x16x32_bf16 v[30:33], v[190:193], v[214:217], v[30:33]
	v_mfma_f32_16x16x32_bf16 v[26:29], v[198:201], v[214:217], v[26:29]
	v_mfma_f32_16x16x32_bf16 v[14:17], v[190:193], v[222:225], v[14:17]
	v_mfma_f32_16x16x32_bf16 v[10:13], v[198:201], v[222:225], v[10:13]
	v_mfma_f32_16x16x32_bf16 v[6:9], v[190:193], v[238:241], v[6:9]
	v_mfma_f32_16x16x32_bf16 v[2:5], v[198:201], v[238:241], v[2:5]
	s_barrier
	s_branch .Lpeel_mid_2138
	.p2align	6
